# unrolled scan loop: slot-release flag written every four groups
# speedup vs baseline: 1.0191x; 1.0049x over previous
.Lc_ret_A0:
	ds_read_b128 v[0:3], v194 offset:8192
	ds_read_b128 v[4:7], v194 offset:6144
	ds_read_b128 v[8:11], v194 offset:6400
	ds_read_b128 v[12:15], v194 offset:7168
	ds_read_b128 v[16:19], v194 offset:7424
	ds_read_b128 v[20:23], v194 offset:8448
	ds_read_b128 v[24:27], v194 offset:6656
	ds_read_b128 v[28:31], v194 offset:6912
	ds_read_b128 v[32:35], v194 offset:7680
	ds_read_b128 v[36:39], v194 offset:7936
	ds_read_b64 v[88:89], v195 offset:8704
	v_fma_mix_f32 v84, v84, v72, v100 op_sel:[0,0,0] op_sel_hi:[0,1,0]
	v_fma_mix_f32 v85, v85, v72, v101 op_sel:[0,1,0] op_sel_hi:[0,1,0]
	v_add_f32_dpp v98, v98, v98 row_half_mirror row_mask:0xf bank_mask:0xf bound_ctrl:1
	v_fma_mix_f32 v86, v86, v73, v102 op_sel:[0,0,0] op_sel_hi:[0,1,0]
	v_fma_mix_f32 v87, v87, v73, v103 op_sel:[0,1,0] op_sel_hi:[0,1,0]
	v_add_f32_dpp v98, v98, v98 row_mirror row_mask:0xf bank_mask:0xf bound_ctrl:1
	v_fma_mix_f32 v84, -v98, v76, v84 op_sel:[0,0,0] op_sel_hi:[0,1,0]
	v_fma_mix_f32 v85, -v98, v76, v85 op_sel:[0,1,0] op_sel_hi:[0,1,0]
	v_fma_mix_f32 v86, -v98, v77, v86 op_sel:[0,0,0] op_sel_hi:[0,1,0]
	v_fma_mix_f32 v87, -v98, v77, v87 op_sel:[0,1,0] op_sel_hi:[0,1,0]
	v_fma_mix_f32 v73, v84, v66, 0 op_sel:[0,0,0] op_sel_hi:[0,1,0]
	v_fma_mix_f32 v97, v84, v56, 0 op_sel:[0,0,0] op_sel_hi:[0,1,0]
	v_fma_mix_f32 v73, v85, v66, v73 op_sel:[0,1,0] op_sel_hi:[0,1,0]
	v_fma_mix_f32 v56, v85, v56, v97 op_sel:[0,1,0] op_sel_hi:[0,1,0]
	v_fma_mix_f32 v73, v86, v67, v73 op_sel:[0,0,0] op_sel_hi:[0,1,0]
	v_fma_mix_f32 v56, v86, v57, v56 op_sel:[0,0,0] op_sel_hi:[0,1,0]
	v_fma_mix_f32 v73, v87, v67, v73 op_sel:[0,1,0] op_sel_hi:[0,1,0]
	v_fma_mix_f32 v56, v87, v57, v56 op_sel:[0,1,0] op_sel_hi:[0,1,0]
	v_fma_mix_f32 v75, v92, v70, 0 op_sel:[1,0,0] op_sel_hi:[1,1,0]
	v_fma_mix_f32 v76, v92, v70, 0 op_sel:[1,1,0] op_sel_hi:[1,1,0]
	v_add_f32_dpp v73, v73, v73 quad_perm:[1,0,3,2] row_mask:0xf bank_mask:0xf bound_ctrl:1
	v_fma_mix_f32 v77, v92, v71, 0 op_sel:[1,0,0] op_sel_hi:[1,1,0]
	v_fma_mix_f32 v78, v92, v71, 0 op_sel:[1,1,0] op_sel_hi:[1,1,0]
	v_add_f32_dpp v73, v73, v73 quad_perm:[2,3,0,1] row_mask:0xf bank_mask:0xf bound_ctrl:1
	v_fma_mix_f32 v84, v84, v64, v75 op_sel:[0,0,0] op_sel_hi:[0,1,0]
	v_fma_mix_f32 v85, v85, v64, v76 op_sel:[0,1,0] op_sel_hi:[0,1,0]
	v_add_f32_dpp v73, v73, v73 row_half_mirror row_mask:0xf bank_mask:0xf bound_ctrl:1
	v_fma_mix_f32 v86, v86, v65, v77 op_sel:[0,0,0] op_sel_hi:[0,1,0]
	v_fma_mix_f32 v87, v87, v65, v78 op_sel:[0,1,0] op_sel_hi:[0,1,0]
	v_add_f32_dpp v73, v73, v73 row_mirror row_mask:0xf bank_mask:0xf bound_ctrl:1
	v_fma_mix_f32 v84, -v73, v68, v84 op_sel:[0,0,0] op_sel_hi:[0,1,0]
	v_fma_mix_f32 v85, -v73, v68, v85 op_sel:[0,1,0] op_sel_hi:[0,1,0]
	v_fma_mix_f32 v86, -v73, v69, v86 op_sel:[0,0,0] op_sel_hi:[0,1,0]
	v_fma_mix_f32 v87, -v73, v69, v87 op_sel:[0,1,0] op_sel_hi:[0,1,0]
	v_fma_mix_f32 v64, v84, v54, 0 op_sel:[0,0,0] op_sel_hi:[0,1,0]
	v_fma_mix_f32 v57, v84, v58, 0 op_sel:[0,0,0] op_sel_hi:[0,1,0]
	v_fma_mix_f32 v64, v85, v54, v64 op_sel:[0,1,0] op_sel_hi:[0,1,0]
	v_fma_mix_f32 v57, v85, v58, v57 op_sel:[0,1,0] op_sel_hi:[0,1,0]
	v_fma_mix_f32 v64, v86, v55, v64 op_sel:[0,0,0] op_sel_hi:[0,1,0]
	v_fma_mix_f32 v57, v86, v59, v57 op_sel:[0,0,0] op_sel_hi:[0,1,0]
	v_fma_mix_f32 v64, v87, v55, v64 op_sel:[0,1,0] op_sel_hi:[0,1,0]
	v_fma_mix_f32 v57, v87, v59, v57 op_sel:[0,1,0] op_sel_hi:[0,1,0]
	v_fma_mix_f32 v66, v93, v62, 0 op_sel:[0,0,0] op_sel_hi:[1,1,0]
	v_fma_mix_f32 v67, v93, v62, 0 op_sel:[0,1,0] op_sel_hi:[1,1,0]
	v_add_f32_dpp v64, v64, v64 quad_perm:[1,0,3,2] row_mask:0xf bank_mask:0xf bound_ctrl:1
	v_fma_mix_f32 v68, v93, v63, 0 op_sel:[0,0,0] op_sel_hi:[1,1,0]
	v_fma_mix_f32 v69, v93, v63, 0 op_sel:[0,1,0] op_sel_hi:[1,1,0]
	v_add_f32_dpp v64, v64, v64 quad_perm:[2,3,0,1] row_mask:0xf bank_mask:0xf bound_ctrl:1
	v_fma_mix_f32 v84, v84, v52, v66 op_sel:[0,0,0] op_sel_hi:[0,1,0]
	v_fma_mix_f32 v85, v85, v52, v67 op_sel:[0,1,0] op_sel_hi:[0,1,0]
	v_add_f32_dpp v64, v64, v64 row_half_mirror row_mask:0xf bank_mask:0xf bound_ctrl:1
	v_fma_mix_f32 v86, v86, v53, v68 op_sel:[0,0,0] op_sel_hi:[0,1,0]
	v_fma_mix_f32 v87, v87, v53, v69 op_sel:[0,1,0] op_sel_hi:[0,1,0]
	v_add_f32_dpp v64, v64, v64 row_mirror row_mask:0xf bank_mask:0xf bound_ctrl:1
	v_fma_mix_f32 v84, -v64, v60, v84 op_sel:[0,0,0] op_sel_hi:[0,1,0]
	v_fma_mix_f32 v85, -v64, v60, v85 op_sel:[0,1,0] op_sel_hi:[0,1,0]
	v_fma_mix_f32 v86, -v64, v61, v86 op_sel:[0,0,0] op_sel_hi:[0,1,0]
	v_fma_mix_f32 v87, -v64, v61, v87 op_sel:[0,1,0] op_sel_hi:[0,1,0]
	v_fma_mix_f32 v53, v84, v46, 0 op_sel:[0,0,0] op_sel_hi:[0,1,0]
	v_fma_mix_f32 v59, v84, v40, 0 op_sel:[0,0,0] op_sel_hi:[0,1,0]
	v_fma_mix_f32 v53, v85, v46, v53 op_sel:[0,1,0] op_sel_hi:[0,1,0]
	v_fma_mix_f32 v40, v85, v40, v59 op_sel:[0,1,0] op_sel_hi:[0,1,0]
	v_fma_mix_f32 v53, v86, v47, v53 op_sel:[0,0,0] op_sel_hi:[0,1,0]
	v_fma_mix_f32 v40, v86, v41, v40 op_sel:[0,0,0] op_sel_hi:[0,1,0]
	v_fma_mix_f32 v53, v87, v47, v53 op_sel:[0,1,0] op_sel_hi:[0,1,0]
	v_fma_mix_f32 v40, v87, v41, v40 op_sel:[0,1,0] op_sel_hi:[0,1,0]
	v_fma_mix_f32 v55, v93, v50, 0 op_sel:[1,0,0] op_sel_hi:[1,1,0]
	v_fma_mix_f32 v58, v93, v50, 0 op_sel:[1,1,0] op_sel_hi:[1,1,0]
	v_add_f32_dpp v53, v53, v53 quad_perm:[1,0,3,2] row_mask:0xf bank_mask:0xf bound_ctrl:1
	v_fma_mix_f32 v59, v93, v51, 0 op_sel:[1,0,0] op_sel_hi:[1,1,0]
	v_fma_mix_f32 v60, v93, v51, 0 op_sel:[1,1,0] op_sel_hi:[1,1,0]
	v_add_f32_dpp v53, v53, v53 quad_perm:[2,3,0,1] row_mask:0xf bank_mask:0xf bound_ctrl:1
	v_fma_mix_f32 v84, v84, v44, v55 op_sel:[0,0,0] op_sel_hi:[0,1,0]
	v_fma_mix_f32 v85, v85, v44, v58 op_sel:[0,1,0] op_sel_hi:[0,1,0]
	v_add_f32_dpp v53, v53, v53 row_half_mirror row_mask:0xf bank_mask:0xf bound_ctrl:1
	v_fma_mix_f32 v86, v86, v45, v59 op_sel:[0,0,0] op_sel_hi:[0,1,0]
	v_fma_mix_f32 v87, v87, v45, v60 op_sel:[0,1,0] op_sel_hi:[0,1,0]
	v_add_f32_dpp v53, v53, v53 row_mirror row_mask:0xf bank_mask:0xf bound_ctrl:1
	v_fma_mix_f32 v84, -v53, v48, v84 op_sel:[0,0,0] op_sel_hi:[0,1,0]
	v_fma_mix_f32 v85, -v53, v48, v85 op_sel:[0,1,0] op_sel_hi:[0,1,0]
	v_fma_mix_f32 v86, -v53, v49, v86 op_sel:[0,0,0] op_sel_hi:[0,1,0]
	v_fma_mix_f32 v87, -v53, v49, v87 op_sel:[0,1,0] op_sel_hi:[0,1,0]
	v_fma_mix_f32 v41, v84, v42, 0 op_sel:[0,0,0] op_sel_hi:[0,1,0]
	v_cndmask_b32_e64 v187, v57, v56, s[38:39]
	v_fma_mix_f32 v41, v85, v42, v41 op_sel:[0,1,0] op_sel_hi:[0,1,0]
	v_cndmask_b32_e64 v188, v56, v57, s[38:39]
	v_fma_mix_f32 v41, v86, v43, v41 op_sel:[0,0,0] op_sel_hi:[0,1,0]
	v_fma_mix_f32 v41, v87, v43, v41 op_sel:[0,1,0] op_sel_hi:[0,1,0]
	v_cndmask_b32_e64 v189, v41, v40, s[38:39]
	v_cndmask_b32_e64 v190, v40, v41, s[38:39]
	s_waitcnt lgkmcnt(0)
	v_fma_mix_f32 v98, v84, v6, 0 op_sel:[0,0,0] op_sel_hi:[0,1,0]
	v_fma_mix_f32 v98, v85, v6, v98 op_sel:[0,1,0] op_sel_hi:[0,1,0]
	v_add_f32_dpp v188, v188, v187 quad_perm:[1,0,3,2] row_mask:0xf bank_mask:0xf bound_ctrl:1
	v_add_f32_dpp v189, v190, v189 quad_perm:[1,0,3,2] row_mask:0xf bank_mask:0xf bound_ctrl:1
	v_fma_mix_f32 v98, v86, v7, v98 op_sel:[0,0,0] op_sel_hi:[0,1,0]
	v_fma_mix_f32 v98, v87, v7, v98 op_sel:[0,1,0] op_sel_hi:[0,1,0]
	v_cndmask_b32_e64 v191, v189, v188, s[40:41]
	v_cndmask_b32_e64 v192, v188, v189, s[40:41]
	v_fma_mix_f32 v100, v88, v14, 0 op_sel:[0,0,0] op_sel_hi:[1,1,0]
	v_fma_mix_f32 v101, v88, v14, 0 op_sel:[0,1,0] op_sel_hi:[1,1,0]
	v_add_f32_dpp v192, v192, v191 quad_perm:[2,3,0,1] row_mask:0xf bank_mask:0xf bound_ctrl:1
	v_add_f32_dpp v98, v98, v98 quad_perm:[1,0,3,2] row_mask:0xf bank_mask:0xf bound_ctrl:1
	v_fma_mix_f32 v102, v88, v15, 0 op_sel:[0,0,0] op_sel_hi:[1,1,0]
	v_add_f32_dpp v192, v192, v192 row_ror:4 row_mask:0xf bank_mask:0xf bound_ctrl:1
	v_fma_mix_f32 v103, v88, v15, 0 op_sel:[0,1,0] op_sel_hi:[1,1,0]
	v_add_f32_dpp v98, v98, v98 quad_perm:[2,3,0,1] row_mask:0xf bank_mask:0xf bound_ctrl:1
	v_add_f32_dpp v192, v192, v192 row_ror:8 row_mask:0xf bank_mask:0xf bound_ctrl:1
	v_cvt_f16_f32_e32 v192, v192
	global_store_short v83, v192, s[36:37]
	s_add_u32 s36, s36, s44
	s_addc_u32 s37, s37, s45
	ds_read_b128 v[56:59], v194 offset:11264
	ds_read_b128 v[72:75], v194 offset:9216
	ds_read_b128 v[64:67], v194 offset:9472
	ds_read_b128 v[76:79], v194 offset:10240
	ds_read_b128 v[68:71], v194 offset:10496
	ds_read_b128 v[40:43], v194 offset:11520
	ds_read_b128 v[52:55], v194 offset:9728
	ds_read_b128 v[44:47], v194 offset:9984
	ds_read_b128 v[60:63], v194 offset:10752
	ds_read_b128 v[48:51], v194 offset:11008
	ds_read_b64 v[92:93], v195 offset:11776
	v_fma_mix_f32 v84, v84, v4, v100 op_sel:[0,0,0] op_sel_hi:[0,1,0]
	v_fma_mix_f32 v85, v85, v4, v101 op_sel:[0,1,0] op_sel_hi:[0,1,0]
	v_add_f32_dpp v98, v98, v98 row_half_mirror row_mask:0xf bank_mask:0xf bound_ctrl:1
	v_fma_mix_f32 v86, v86, v5, v102 op_sel:[0,0,0] op_sel_hi:[0,1,0]
	v_fma_mix_f32 v87, v87, v5, v103 op_sel:[0,1,0] op_sel_hi:[0,1,0]
	v_add_f32_dpp v98, v98, v98 row_mirror row_mask:0xf bank_mask:0xf bound_ctrl:1
	v_fma_mix_f32 v84, -v98, v12, v84 op_sel:[0,0,0] op_sel_hi:[0,1,0]
	v_fma_mix_f32 v85, -v98, v12, v85 op_sel:[0,1,0] op_sel_hi:[0,1,0]
	v_fma_mix_f32 v86, -v98, v13, v86 op_sel:[0,0,0] op_sel_hi:[0,1,0]
	v_fma_mix_f32 v87, -v98, v13, v87 op_sel:[0,1,0] op_sel_hi:[0,1,0]
	v_fma_mix_f32 v99, v84, v10, 0 op_sel:[0,0,0] op_sel_hi:[0,1,0]
	v_fma_mix_f32 v96, v84, v0, 0 op_sel:[0,0,0] op_sel_hi:[0,1,0]
	v_fma_mix_f32 v99, v85, v10, v99 op_sel:[0,1,0] op_sel_hi:[0,1,0]
	v_fma_mix_f32 v96, v85, v0, v96 op_sel:[0,1,0] op_sel_hi:[0,1,0]
	v_fma_mix_f32 v99, v86, v11, v99 op_sel:[0,0,0] op_sel_hi:[0,1,0]
	v_fma_mix_f32 v96, v86, v1, v96 op_sel:[0,0,0] op_sel_hi:[0,1,0]
	v_fma_mix_f32 v99, v87, v11, v99 op_sel:[0,1,0] op_sel_hi:[0,1,0]
	v_fma_mix_f32 v96, v87, v1, v96 op_sel:[0,1,0] op_sel_hi:[0,1,0]
	v_fma_mix_f32 v101, v88, v18, 0 op_sel:[1,0,0] op_sel_hi:[1,1,0]
	v_fma_mix_f32 v102, v88, v18, 0 op_sel:[1,1,0] op_sel_hi:[1,1,0]
	v_add_f32_dpp v99, v99, v99 quad_perm:[1,0,3,2] row_mask:0xf bank_mask:0xf bound_ctrl:1
	v_fma_mix_f32 v103, v88, v19, 0 op_sel:[1,0,0] op_sel_hi:[1,1,0]
	v_fma_mix_f32 v104, v88, v19, 0 op_sel:[1,1,0] op_sel_hi:[1,1,0]
	v_add_f32_dpp v99, v99, v99 quad_perm:[2,3,0,1] row_mask:0xf bank_mask:0xf bound_ctrl:1
	v_fma_mix_f32 v84, v84, v8, v101 op_sel:[0,0,0] op_sel_hi:[0,1,0]
	v_fma_mix_f32 v85, v85, v8, v102 op_sel:[0,1,0] op_sel_hi:[0,1,0]
	v_add_f32_dpp v99, v99, v99 row_half_mirror row_mask:0xf bank_mask:0xf bound_ctrl:1
	v_fma_mix_f32 v86, v86, v9, v103 op_sel:[0,0,0] op_sel_hi:[0,1,0]
	v_fma_mix_f32 v87, v87, v9, v104 op_sel:[0,1,0] op_sel_hi:[0,1,0]
	v_add_f32_dpp v99, v99, v99 row_mirror row_mask:0xf bank_mask:0xf bound_ctrl:1
	v_fma_mix_f32 v84, -v99, v16, v84 op_sel:[0,0,0] op_sel_hi:[0,1,0]
	v_fma_mix_f32 v85, -v99, v16, v85 op_sel:[0,1,0] op_sel_hi:[0,1,0]
	v_fma_mix_f32 v86, -v99, v17, v86 op_sel:[0,0,0] op_sel_hi:[0,1,0]
	v_fma_mix_f32 v87, -v99, v17, v87 op_sel:[0,1,0] op_sel_hi:[0,1,0]
	v_fma_mix_f32 v100, v84, v26, 0 op_sel:[0,0,0] op_sel_hi:[0,1,0]
	v_fma_mix_f32 v97, v84, v2, 0 op_sel:[0,0,0] op_sel_hi:[0,1,0]
	v_fma_mix_f32 v100, v85, v26, v100 op_sel:[0,1,0] op_sel_hi:[0,1,0]
	v_fma_mix_f32 v97, v85, v2, v97 op_sel:[0,1,0] op_sel_hi:[0,1,0]
	v_fma_mix_f32 v100, v86, v27, v100 op_sel:[0,0,0] op_sel_hi:[0,1,0]
	v_fma_mix_f32 v97, v86, v3, v97 op_sel:[0,0,0] op_sel_hi:[0,1,0]
	v_fma_mix_f32 v100, v87, v27, v100 op_sel:[0,1,0] op_sel_hi:[0,1,0]
	v_fma_mix_f32 v97, v87, v3, v97 op_sel:[0,1,0] op_sel_hi:[0,1,0]
	v_fma_mix_f32 v102, v89, v34, 0 op_sel:[0,0,0] op_sel_hi:[1,1,0]
	v_fma_mix_f32 v103, v89, v34, 0 op_sel:[0,1,0] op_sel_hi:[1,1,0]
	v_add_f32_dpp v100, v100, v100 quad_perm:[1,0,3,2] row_mask:0xf bank_mask:0xf bound_ctrl:1
	v_fma_mix_f32 v104, v89, v35, 0 op_sel:[0,0,0] op_sel_hi:[1,1,0]
	v_fma_mix_f32 v105, v89, v35, 0 op_sel:[0,1,0] op_sel_hi:[1,1,0]
	v_add_f32_dpp v100, v100, v100 quad_perm:[2,3,0,1] row_mask:0xf bank_mask:0xf bound_ctrl:1
	v_fma_mix_f32 v84, v84, v24, v102 op_sel:[0,0,0] op_sel_hi:[0,1,0]
	v_fma_mix_f32 v85, v85, v24, v103 op_sel:[0,1,0] op_sel_hi:[0,1,0]
	v_add_f32_dpp v100, v100, v100 row_half_mirror row_mask:0xf bank_mask:0xf bound_ctrl:1
	v_fma_mix_f32 v86, v86, v25, v104 op_sel:[0,0,0] op_sel_hi:[0,1,0]
	v_fma_mix_f32 v87, v87, v25, v105 op_sel:[0,1,0] op_sel_hi:[0,1,0]
	v_add_f32_dpp v100, v100, v100 row_mirror row_mask:0xf bank_mask:0xf bound_ctrl:1
	v_fma_mix_f32 v84, -v100, v32, v84 op_sel:[0,0,0] op_sel_hi:[0,1,0]
	v_fma_mix_f32 v85, -v100, v32, v85 op_sel:[0,1,0] op_sel_hi:[0,1,0]
	v_fma_mix_f32 v86, -v100, v33, v86 op_sel:[0,0,0] op_sel_hi:[0,1,0]
	v_fma_mix_f32 v87, -v100, v33, v87 op_sel:[0,1,0] op_sel_hi:[0,1,0]
	v_fma_mix_f32 v101, v84, v30, 0 op_sel:[0,0,0] op_sel_hi:[0,1,0]
	v_fma_mix_f32 v98, v84, v20, 0 op_sel:[0,0,0] op_sel_hi:[0,1,0]
	v_fma_mix_f32 v101, v85, v30, v101 op_sel:[0,1,0] op_sel_hi:[0,1,0]
	v_fma_mix_f32 v98, v85, v20, v98 op_sel:[0,1,0] op_sel_hi:[0,1,0]
	v_fma_mix_f32 v101, v86, v31, v101 op_sel:[0,0,0] op_sel_hi:[0,1,0]
	v_fma_mix_f32 v98, v86, v21, v98 op_sel:[0,0,0] op_sel_hi:[0,1,0]
	v_fma_mix_f32 v101, v87, v31, v101 op_sel:[0,1,0] op_sel_hi:[0,1,0]
	v_fma_mix_f32 v98, v87, v21, v98 op_sel:[0,1,0] op_sel_hi:[0,1,0]
	v_fma_mix_f32 v103, v89, v38, 0 op_sel:[1,0,0] op_sel_hi:[1,1,0]
	v_fma_mix_f32 v104, v89, v38, 0 op_sel:[1,1,0] op_sel_hi:[1,1,0]
	v_add_f32_dpp v101, v101, v101 quad_perm:[1,0,3,2] row_mask:0xf bank_mask:0xf bound_ctrl:1
	v_fma_mix_f32 v105, v89, v39, 0 op_sel:[1,0,0] op_sel_hi:[1,1,0]
	v_fma_mix_f32 v119, v89, v39, 0 op_sel:[1,1,0] op_sel_hi:[1,1,0]
	v_add_f32_dpp v101, v101, v101 quad_perm:[2,3,0,1] row_mask:0xf bank_mask:0xf bound_ctrl:1
	v_fma_mix_f32 v84, v84, v28, v103 op_sel:[0,0,0] op_sel_hi:[0,1,0]
	v_fma_mix_f32 v85, v85, v28, v104 op_sel:[0,1,0] op_sel_hi:[0,1,0]
	v_add_f32_dpp v101, v101, v101 row_half_mirror row_mask:0xf bank_mask:0xf bound_ctrl:1
	v_fma_mix_f32 v86, v86, v29, v105 op_sel:[0,0,0] op_sel_hi:[0,1,0]
	v_fma_mix_f32 v87, v87, v29, v119 op_sel:[0,1,0] op_sel_hi:[0,1,0]
	v_add_f32_dpp v101, v101, v101 row_mirror row_mask:0xf bank_mask:0xf bound_ctrl:1
	v_fma_mix_f32 v84, -v101, v36, v84 op_sel:[0,0,0] op_sel_hi:[0,1,0]
	v_fma_mix_f32 v85, -v101, v36, v85 op_sel:[0,1,0] op_sel_hi:[0,1,0]
	v_fma_mix_f32 v86, -v101, v37, v86 op_sel:[0,0,0] op_sel_hi:[0,1,0]
	v_fma_mix_f32 v87, -v101, v37, v87 op_sel:[0,1,0] op_sel_hi:[0,1,0]
	v_fma_mix_f32 v99, v84, v22, 0 op_sel:[0,0,0] op_sel_hi:[0,1,0]
	v_cndmask_b32_e64 v187, v97, v96, s[38:39]
	v_fma_mix_f32 v99, v85, v22, v99 op_sel:[0,1,0] op_sel_hi:[0,1,0]
	v_cndmask_b32_e64 v188, v96, v97, s[38:39]
	v_fma_mix_f32 v99, v86, v23, v99 op_sel:[0,0,0] op_sel_hi:[0,1,0]
	v_fma_mix_f32 v99, v87, v23, v99 op_sel:[0,1,0] op_sel_hi:[0,1,0]
	v_cndmask_b32_e64 v189, v99, v98, s[38:39]
	v_cndmask_b32_e64 v190, v98, v99, s[38:39]
	s_waitcnt lgkmcnt(0)
	v_fma_mix_f32 v98, v84, v74, 0 op_sel:[0,0,0] op_sel_hi:[0,1,0]
	v_fma_mix_f32 v98, v85, v74, v98 op_sel:[0,1,0] op_sel_hi:[0,1,0]
	v_add_f32_dpp v188, v188, v187 quad_perm:[1,0,3,2] row_mask:0xf bank_mask:0xf bound_ctrl:1
	v_add_f32_dpp v189, v190, v189 quad_perm:[1,0,3,2] row_mask:0xf bank_mask:0xf bound_ctrl:1
	v_fma_mix_f32 v98, v86, v75, v98 op_sel:[0,0,0] op_sel_hi:[0,1,0]
	v_fma_mix_f32 v98, v87, v75, v98 op_sel:[0,1,0] op_sel_hi:[0,1,0]
	v_cndmask_b32_e64 v191, v189, v188, s[40:41]
	v_cndmask_b32_e64 v192, v188, v189, s[40:41]
	v_fma_mix_f32 v100, v92, v78, 0 op_sel:[0,0,0] op_sel_hi:[1,1,0]
	v_fma_mix_f32 v101, v92, v78, 0 op_sel:[0,1,0] op_sel_hi:[1,1,0]
	v_add_f32_dpp v192, v192, v191 quad_perm:[2,3,0,1] row_mask:0xf bank_mask:0xf bound_ctrl:1
	v_add_f32_dpp v98, v98, v98 quad_perm:[1,0,3,2] row_mask:0xf bank_mask:0xf bound_ctrl:1
	v_fma_mix_f32 v102, v92, v79, 0 op_sel:[0,0,0] op_sel_hi:[1,1,0]
	v_add_f32_dpp v192, v192, v192 row_ror:4 row_mask:0xf bank_mask:0xf bound_ctrl:1
	v_fma_mix_f32 v103, v92, v79, 0 op_sel:[0,1,0] op_sel_hi:[1,1,0]
	v_add_f32_dpp v98, v98, v98 quad_perm:[2,3,0,1] row_mask:0xf bank_mask:0xf bound_ctrl:1
	v_add_f32_dpp v192, v192, v192 row_ror:8 row_mask:0xf bank_mask:0xf bound_ctrl:1
	v_cvt_f16_f32_e32 v192, v192
	global_store_short v83, v192, s[36:37]
	s_add_u32 s36, s36, s44
	s_addc_u32 s37, s37, s45
	s_cmp_gt_i32 s35, 5
	s_cbranch_scc0 .Lc_poll_A1

.Lc_ret_A2:
	ds_read_b128 v[0:3], v194 offset:20480
	ds_read_b128 v[4:7], v194 offset:18432
	ds_read_b128 v[8:11], v194 offset:18688
	ds_read_b128 v[12:15], v194 offset:19456
	ds_read_b128 v[16:19], v194 offset:19712
	ds_read_b128 v[20:23], v194 offset:20736
	ds_read_b128 v[24:27], v194 offset:18944
	ds_read_b128 v[28:31], v194 offset:19200
	ds_read_b128 v[32:35], v194 offset:19968
	ds_read_b128 v[36:39], v194 offset:20224
	ds_read_b64 v[88:89], v195 offset:20992
	v_fma_mix_f32 v84, v84, v72, v100 op_sel:[0,0,0] op_sel_hi:[0,1,0]
	v_fma_mix_f32 v85, v85, v72, v101 op_sel:[0,1,0] op_sel_hi:[0,1,0]
	v_add_f32_dpp v98, v98, v98 row_half_mirror row_mask:0xf bank_mask:0xf bound_ctrl:1
	v_fma_mix_f32 v86, v86, v73, v102 op_sel:[0,0,0] op_sel_hi:[0,1,0]
	v_fma_mix_f32 v87, v87, v73, v103 op_sel:[0,1,0] op_sel_hi:[0,1,0]
	v_add_f32_dpp v98, v98, v98 row_mirror row_mask:0xf bank_mask:0xf bound_ctrl:1
	v_fma_mix_f32 v84, -v98, v76, v84 op_sel:[0,0,0] op_sel_hi:[0,1,0]
	v_fma_mix_f32 v85, -v98, v76, v85 op_sel:[0,1,0] op_sel_hi:[0,1,0]
	v_fma_mix_f32 v86, -v98, v77, v86 op_sel:[0,0,0] op_sel_hi:[0,1,0]
	v_fma_mix_f32 v87, -v98, v77, v87 op_sel:[0,1,0] op_sel_hi:[0,1,0]
	v_fma_mix_f32 v73, v84, v66, 0 op_sel:[0,0,0] op_sel_hi:[0,1,0]
	v_fma_mix_f32 v97, v84, v56, 0 op_sel:[0,0,0] op_sel_hi:[0,1,0]
	v_fma_mix_f32 v73, v85, v66, v73 op_sel:[0,1,0] op_sel_hi:[0,1,0]
	v_fma_mix_f32 v56, v85, v56, v97 op_sel:[0,1,0] op_sel_hi:[0,1,0]
	v_fma_mix_f32 v73, v86, v67, v73 op_sel:[0,0,0] op_sel_hi:[0,1,0]
	v_fma_mix_f32 v56, v86, v57, v56 op_sel:[0,0,0] op_sel_hi:[0,1,0]
	v_fma_mix_f32 v73, v87, v67, v73 op_sel:[0,1,0] op_sel_hi:[0,1,0]
	v_fma_mix_f32 v56, v87, v57, v56 op_sel:[0,1,0] op_sel_hi:[0,1,0]
	v_fma_mix_f32 v75, v92, v70, 0 op_sel:[1,0,0] op_sel_hi:[1,1,0]
	v_fma_mix_f32 v76, v92, v70, 0 op_sel:[1,1,0] op_sel_hi:[1,1,0]
	v_add_f32_dpp v73, v73, v73 quad_perm:[1,0,3,2] row_mask:0xf bank_mask:0xf bound_ctrl:1
	v_fma_mix_f32 v77, v92, v71, 0 op_sel:[1,0,0] op_sel_hi:[1,1,0]
	v_fma_mix_f32 v78, v92, v71, 0 op_sel:[1,1,0] op_sel_hi:[1,1,0]
	v_add_f32_dpp v73, v73, v73 quad_perm:[2,3,0,1] row_mask:0xf bank_mask:0xf bound_ctrl:1
	v_fma_mix_f32 v84, v84, v64, v75 op_sel:[0,0,0] op_sel_hi:[0,1,0]
	v_fma_mix_f32 v85, v85, v64, v76 op_sel:[0,1,0] op_sel_hi:[0,1,0]
	v_add_f32_dpp v73, v73, v73 row_half_mirror row_mask:0xf bank_mask:0xf bound_ctrl:1
	v_fma_mix_f32 v86, v86, v65, v77 op_sel:[0,0,0] op_sel_hi:[0,1,0]
	v_fma_mix_f32 v87, v87, v65, v78 op_sel:[0,1,0] op_sel_hi:[0,1,0]
	v_add_f32_dpp v73, v73, v73 row_mirror row_mask:0xf bank_mask:0xf bound_ctrl:1
	v_fma_mix_f32 v84, -v73, v68, v84 op_sel:[0,0,0] op_sel_hi:[0,1,0]
	v_fma_mix_f32 v85, -v73, v68, v85 op_sel:[0,1,0] op_sel_hi:[0,1,0]
	v_fma_mix_f32 v86, -v73, v69, v86 op_sel:[0,0,0] op_sel_hi:[0,1,0]
	v_fma_mix_f32 v87, -v73, v69, v87 op_sel:[0,1,0] op_sel_hi:[0,1,0]
	v_fma_mix_f32 v64, v84, v54, 0 op_sel:[0,0,0] op_sel_hi:[0,1,0]
	v_fma_mix_f32 v57, v84, v58, 0 op_sel:[0,0,0] op_sel_hi:[0,1,0]
	v_fma_mix_f32 v64, v85, v54, v64 op_sel:[0,1,0] op_sel_hi:[0,1,0]
	v_fma_mix_f32 v57, v85, v58, v57 op_sel:[0,1,0] op_sel_hi:[0,1,0]
	v_fma_mix_f32 v64, v86, v55, v64 op_sel:[0,0,0] op_sel_hi:[0,1,0]
	v_fma_mix_f32 v57, v86, v59, v57 op_sel:[0,0,0] op_sel_hi:[0,1,0]
	v_fma_mix_f32 v64, v87, v55, v64 op_sel:[0,1,0] op_sel_hi:[0,1,0]
	v_fma_mix_f32 v57, v87, v59, v57 op_sel:[0,1,0] op_sel_hi:[0,1,0]
	v_fma_mix_f32 v66, v93, v62, 0 op_sel:[0,0,0] op_sel_hi:[1,1,0]
	v_fma_mix_f32 v67, v93, v62, 0 op_sel:[0,1,0] op_sel_hi:[1,1,0]
	v_add_f32_dpp v64, v64, v64 quad_perm:[1,0,3,2] row_mask:0xf bank_mask:0xf bound_ctrl:1
	v_fma_mix_f32 v68, v93, v63, 0 op_sel:[0,0,0] op_sel_hi:[1,1,0]
	v_fma_mix_f32 v69, v93, v63, 0 op_sel:[0,1,0] op_sel_hi:[1,1,0]
	v_add_f32_dpp v64, v64, v64 quad_perm:[2,3,0,1] row_mask:0xf bank_mask:0xf bound_ctrl:1
	v_fma_mix_f32 v84, v84, v52, v66 op_sel:[0,0,0] op_sel_hi:[0,1,0]
	v_fma_mix_f32 v85, v85, v52, v67 op_sel:[0,1,0] op_sel_hi:[0,1,0]
	v_add_f32_dpp v64, v64, v64 row_half_mirror row_mask:0xf bank_mask:0xf bound_ctrl:1
	v_fma_mix_f32 v86, v86, v53, v68 op_sel:[0,0,0] op_sel_hi:[0,1,0]
	v_fma_mix_f32 v87, v87, v53, v69 op_sel:[0,1,0] op_sel_hi:[0,1,0]
	v_add_f32_dpp v64, v64, v64 row_mirror row_mask:0xf bank_mask:0xf bound_ctrl:1
	v_fma_mix_f32 v84, -v64, v60, v84 op_sel:[0,0,0] op_sel_hi:[0,1,0]
	v_fma_mix_f32 v85, -v64, v60, v85 op_sel:[0,1,0] op_sel_hi:[0,1,0]
	v_fma_mix_f32 v86, -v64, v61, v86 op_sel:[0,0,0] op_sel_hi:[0,1,0]
	v_fma_mix_f32 v87, -v64, v61, v87 op_sel:[0,1,0] op_sel_hi:[0,1,0]
	v_fma_mix_f32 v53, v84, v46, 0 op_sel:[0,0,0] op_sel_hi:[0,1,0]
	v_fma_mix_f32 v59, v84, v40, 0 op_sel:[0,0,0] op_sel_hi:[0,1,0]
	v_fma_mix_f32 v53, v85, v46, v53 op_sel:[0,1,0] op_sel_hi:[0,1,0]
	v_fma_mix_f32 v40, v85, v40, v59 op_sel:[0,1,0] op_sel_hi:[0,1,0]
	v_fma_mix_f32 v53, v86, v47, v53 op_sel:[0,0,0] op_sel_hi:[0,1,0]
	v_fma_mix_f32 v40, v86, v41, v40 op_sel:[0,0,0] op_sel_hi:[0,1,0]
	v_fma_mix_f32 v53, v87, v47, v53 op_sel:[0,1,0] op_sel_hi:[0,1,0]
	v_fma_mix_f32 v40, v87, v41, v40 op_sel:[0,1,0] op_sel_hi:[0,1,0]
	v_fma_mix_f32 v55, v93, v50, 0 op_sel:[1,0,0] op_sel_hi:[1,1,0]
	v_fma_mix_f32 v58, v93, v50, 0 op_sel:[1,1,0] op_sel_hi:[1,1,0]
	v_add_f32_dpp v53, v53, v53 quad_perm:[1,0,3,2] row_mask:0xf bank_mask:0xf bound_ctrl:1
	v_fma_mix_f32 v59, v93, v51, 0 op_sel:[1,0,0] op_sel_hi:[1,1,0]
	v_fma_mix_f32 v60, v93, v51, 0 op_sel:[1,1,0] op_sel_hi:[1,1,0]
	v_add_f32_dpp v53, v53, v53 quad_perm:[2,3,0,1] row_mask:0xf bank_mask:0xf bound_ctrl:1
	v_fma_mix_f32 v84, v84, v44, v55 op_sel:[0,0,0] op_sel_hi:[0,1,0]
	v_fma_mix_f32 v85, v85, v44, v58 op_sel:[0,1,0] op_sel_hi:[0,1,0]
	v_add_f32_dpp v53, v53, v53 row_half_mirror row_mask:0xf bank_mask:0xf bound_ctrl:1
	v_fma_mix_f32 v86, v86, v45, v59 op_sel:[0,0,0] op_sel_hi:[0,1,0]
	v_fma_mix_f32 v87, v87, v45, v60 op_sel:[0,1,0] op_sel_hi:[0,1,0]
	v_add_f32_dpp v53, v53, v53 row_mirror row_mask:0xf bank_mask:0xf bound_ctrl:1
	v_fma_mix_f32 v84, -v53, v48, v84 op_sel:[0,0,0] op_sel_hi:[0,1,0]
	v_fma_mix_f32 v85, -v53, v48, v85 op_sel:[0,1,0] op_sel_hi:[0,1,0]
	v_fma_mix_f32 v86, -v53, v49, v86 op_sel:[0,0,0] op_sel_hi:[0,1,0]
	v_fma_mix_f32 v87, -v53, v49, v87 op_sel:[0,1,0] op_sel_hi:[0,1,0]
	v_fma_mix_f32 v41, v84, v42, 0 op_sel:[0,0,0] op_sel_hi:[0,1,0]
	v_cndmask_b32_e64 v187, v57, v56, s[38:39]
	v_fma_mix_f32 v41, v85, v42, v41 op_sel:[0,1,0] op_sel_hi:[0,1,0]
	v_cndmask_b32_e64 v188, v56, v57, s[38:39]
	v_fma_mix_f32 v41, v86, v43, v41 op_sel:[0,0,0] op_sel_hi:[0,1,0]
	v_fma_mix_f32 v41, v87, v43, v41 op_sel:[0,1,0] op_sel_hi:[0,1,0]
	v_cndmask_b32_e64 v189, v41, v40, s[38:39]
	v_cndmask_b32_e64 v190, v40, v41, s[38:39]
	s_waitcnt lgkmcnt(0)
	v_fma_mix_f32 v98, v84, v6, 0 op_sel:[0,0,0] op_sel_hi:[0,1,0]
	v_fma_mix_f32 v98, v85, v6, v98 op_sel:[0,1,0] op_sel_hi:[0,1,0]
	v_add_f32_dpp v188, v188, v187 quad_perm:[1,0,3,2] row_mask:0xf bank_mask:0xf bound_ctrl:1
	v_add_f32_dpp v189, v190, v189 quad_perm:[1,0,3,2] row_mask:0xf bank_mask:0xf bound_ctrl:1
	v_fma_mix_f32 v98, v86, v7, v98 op_sel:[0,0,0] op_sel_hi:[0,1,0]
	v_fma_mix_f32 v98, v87, v7, v98 op_sel:[0,1,0] op_sel_hi:[0,1,0]
	v_cndmask_b32_e64 v191, v189, v188, s[40:41]
	v_cndmask_b32_e64 v192, v188, v189, s[40:41]
	v_fma_mix_f32 v100, v88, v14, 0 op_sel:[0,0,0] op_sel_hi:[1,1,0]
	v_fma_mix_f32 v101, v88, v14, 0 op_sel:[0,1,0] op_sel_hi:[1,1,0]
	v_add_f32_dpp v192, v192, v191 quad_perm:[2,3,0,1] row_mask:0xf bank_mask:0xf bound_ctrl:1
	v_add_f32_dpp v98, v98, v98 quad_perm:[1,0,3,2] row_mask:0xf bank_mask:0xf bound_ctrl:1
	v_fma_mix_f32 v102, v88, v15, 0 op_sel:[0,0,0] op_sel_hi:[1,1,0]
	v_add_f32_dpp v192, v192, v192 row_ror:4 row_mask:0xf bank_mask:0xf bound_ctrl:1
	v_fma_mix_f32 v103, v88, v15, 0 op_sel:[0,1,0] op_sel_hi:[1,1,0]
	v_add_f32_dpp v98, v98, v98 quad_perm:[2,3,0,1] row_mask:0xf bank_mask:0xf bound_ctrl:1
	v_add_f32_dpp v192, v192, v192 row_ror:8 row_mask:0xf bank_mask:0xf bound_ctrl:1
	v_cvt_f16_f32_e32 v192, v192
	global_store_short v83, v192, s[36:37]
	s_add_u32 s36, s36, s44
	s_addc_u32 s37, s37, s45
	ds_read_b128 v[56:59], v194 offset:23552
	ds_read_b128 v[72:75], v194 offset:21504
	ds_read_b128 v[64:67], v194 offset:21760
	ds_read_b128 v[76:79], v194 offset:22528
	ds_read_b128 v[68:71], v194 offset:22784
	ds_read_b128 v[40:43], v194 offset:23808
	ds_read_b128 v[52:55], v194 offset:22016
	ds_read_b128 v[44:47], v194 offset:22272
	ds_read_b128 v[60:63], v194 offset:23040
	ds_read_b128 v[48:51], v194 offset:23296
	ds_read_b64 v[92:93], v195 offset:24064
	v_fma_mix_f32 v84, v84, v4, v100 op_sel:[0,0,0] op_sel_hi:[0,1,0]
	v_fma_mix_f32 v85, v85, v4, v101 op_sel:[0,1,0] op_sel_hi:[0,1,0]
	v_add_f32_dpp v98, v98, v98 row_half_mirror row_mask:0xf bank_mask:0xf bound_ctrl:1
	v_fma_mix_f32 v86, v86, v5, v102 op_sel:[0,0,0] op_sel_hi:[0,1,0]
	v_fma_mix_f32 v87, v87, v5, v103 op_sel:[0,1,0] op_sel_hi:[0,1,0]
	v_add_f32_dpp v98, v98, v98 row_mirror row_mask:0xf bank_mask:0xf bound_ctrl:1
	v_fma_mix_f32 v84, -v98, v12, v84 op_sel:[0,0,0] op_sel_hi:[0,1,0]
	v_fma_mix_f32 v85, -v98, v12, v85 op_sel:[0,1,0] op_sel_hi:[0,1,0]
	v_fma_mix_f32 v86, -v98, v13, v86 op_sel:[0,0,0] op_sel_hi:[0,1,0]
	v_fma_mix_f32 v87, -v98, v13, v87 op_sel:[0,1,0] op_sel_hi:[0,1,0]
	v_fma_mix_f32 v99, v84, v10, 0 op_sel:[0,0,0] op_sel_hi:[0,1,0]
	v_fma_mix_f32 v96, v84, v0, 0 op_sel:[0,0,0] op_sel_hi:[0,1,0]
	v_fma_mix_f32 v99, v85, v10, v99 op_sel:[0,1,0] op_sel_hi:[0,1,0]
	v_fma_mix_f32 v96, v85, v0, v96 op_sel:[0,1,0] op_sel_hi:[0,1,0]
	v_fma_mix_f32 v99, v86, v11, v99 op_sel:[0,0,0] op_sel_hi:[0,1,0]
	v_fma_mix_f32 v96, v86, v1, v96 op_sel:[0,0,0] op_sel_hi:[0,1,0]
	v_fma_mix_f32 v99, v87, v11, v99 op_sel:[0,1,0] op_sel_hi:[0,1,0]
	v_fma_mix_f32 v96, v87, v1, v96 op_sel:[0,1,0] op_sel_hi:[0,1,0]
	v_fma_mix_f32 v101, v88, v18, 0 op_sel:[1,0,0] op_sel_hi:[1,1,0]
	v_fma_mix_f32 v102, v88, v18, 0 op_sel:[1,1,0] op_sel_hi:[1,1,0]
	v_add_f32_dpp v99, v99, v99 quad_perm:[1,0,3,2] row_mask:0xf bank_mask:0xf bound_ctrl:1
	v_fma_mix_f32 v103, v88, v19, 0 op_sel:[1,0,0] op_sel_hi:[1,1,0]
	v_fma_mix_f32 v104, v88, v19, 0 op_sel:[1,1,0] op_sel_hi:[1,1,0]
	v_add_f32_dpp v99, v99, v99 quad_perm:[2,3,0,1] row_mask:0xf bank_mask:0xf bound_ctrl:1
	v_fma_mix_f32 v84, v84, v8, v101 op_sel:[0,0,0] op_sel_hi:[0,1,0]
	v_fma_mix_f32 v85, v85, v8, v102 op_sel:[0,1,0] op_sel_hi:[0,1,0]
	v_add_f32_dpp v99, v99, v99 row_half_mirror row_mask:0xf bank_mask:0xf bound_ctrl:1
	v_fma_mix_f32 v86, v86, v9, v103 op_sel:[0,0,0] op_sel_hi:[0,1,0]
	v_fma_mix_f32 v87, v87, v9, v104 op_sel:[0,1,0] op_sel_hi:[0,1,0]
	v_add_f32_dpp v99, v99, v99 row_mirror row_mask:0xf bank_mask:0xf bound_ctrl:1
	v_fma_mix_f32 v84, -v99, v16, v84 op_sel:[0,0,0] op_sel_hi:[0,1,0]
	v_fma_mix_f32 v85, -v99, v16, v85 op_sel:[0,1,0] op_sel_hi:[0,1,0]
	v_fma_mix_f32 v86, -v99, v17, v86 op_sel:[0,0,0] op_sel_hi:[0,1,0]
	v_fma_mix_f32 v87, -v99, v17, v87 op_sel:[0,1,0] op_sel_hi:[0,1,0]
	v_fma_mix_f32 v100, v84, v26, 0 op_sel:[0,0,0] op_sel_hi:[0,1,0]
	v_fma_mix_f32 v97, v84, v2, 0 op_sel:[0,0,0] op_sel_hi:[0,1,0]
	v_fma_mix_f32 v100, v85, v26, v100 op_sel:[0,1,0] op_sel_hi:[0,1,0]
	v_fma_mix_f32 v97, v85, v2, v97 op_sel:[0,1,0] op_sel_hi:[0,1,0]
	v_fma_mix_f32 v100, v86, v27, v100 op_sel:[0,0,0] op_sel_hi:[0,1,0]
	v_fma_mix_f32 v97, v86, v3, v97 op_sel:[0,0,0] op_sel_hi:[0,1,0]
	v_fma_mix_f32 v100, v87, v27, v100 op_sel:[0,1,0] op_sel_hi:[0,1,0]
	v_fma_mix_f32 v97, v87, v3, v97 op_sel:[0,1,0] op_sel_hi:[0,1,0]
	v_fma_mix_f32 v102, v89, v34, 0 op_sel:[0,0,0] op_sel_hi:[1,1,0]
	v_fma_mix_f32 v103, v89, v34, 0 op_sel:[0,1,0] op_sel_hi:[1,1,0]
	v_add_f32_dpp v100, v100, v100 quad_perm:[1,0,3,2] row_mask:0xf bank_mask:0xf bound_ctrl:1
	v_fma_mix_f32 v104, v89, v35, 0 op_sel:[0,0,0] op_sel_hi:[1,1,0]
	v_fma_mix_f32 v105, v89, v35, 0 op_sel:[0,1,0] op_sel_hi:[1,1,0]
	v_add_f32_dpp v100, v100, v100 quad_perm:[2,3,0,1] row_mask:0xf bank_mask:0xf bound_ctrl:1
	v_fma_mix_f32 v84, v84, v24, v102 op_sel:[0,0,0] op_sel_hi:[0,1,0]
	v_fma_mix_f32 v85, v85, v24, v103 op_sel:[0,1,0] op_sel_hi:[0,1,0]
	v_add_f32_dpp v100, v100, v100 row_half_mirror row_mask:0xf bank_mask:0xf bound_ctrl:1
	v_fma_mix_f32 v86, v86, v25, v104 op_sel:[0,0,0] op_sel_hi:[0,1,0]
	v_fma_mix_f32 v87, v87, v25, v105 op_sel:[0,1,0] op_sel_hi:[0,1,0]
	v_add_f32_dpp v100, v100, v100 row_mirror row_mask:0xf bank_mask:0xf bound_ctrl:1
	v_fma_mix_f32 v84, -v100, v32, v84 op_sel:[0,0,0] op_sel_hi:[0,1,0]
	v_fma_mix_f32 v85, -v100, v32, v85 op_sel:[0,1,0] op_sel_hi:[0,1,0]
	v_fma_mix_f32 v86, -v100, v33, v86 op_sel:[0,0,0] op_sel_hi:[0,1,0]
	v_fma_mix_f32 v87, -v100, v33, v87 op_sel:[0,1,0] op_sel_hi:[0,1,0]
	v_fma_mix_f32 v101, v84, v30, 0 op_sel:[0,0,0] op_sel_hi:[0,1,0]
	v_fma_mix_f32 v98, v84, v20, 0 op_sel:[0,0,0] op_sel_hi:[0,1,0]
	v_fma_mix_f32 v101, v85, v30, v101 op_sel:[0,1,0] op_sel_hi:[0,1,0]
	v_fma_mix_f32 v98, v85, v20, v98 op_sel:[0,1,0] op_sel_hi:[0,1,0]
	v_fma_mix_f32 v101, v86, v31, v101 op_sel:[0,0,0] op_sel_hi:[0,1,0]
	v_fma_mix_f32 v98, v86, v21, v98 op_sel:[0,0,0] op_sel_hi:[0,1,0]
	v_fma_mix_f32 v101, v87, v31, v101 op_sel:[0,1,0] op_sel_hi:[0,1,0]
	v_fma_mix_f32 v98, v87, v21, v98 op_sel:[0,1,0] op_sel_hi:[0,1,0]
	v_fma_mix_f32 v103, v89, v38, 0 op_sel:[1,0,0] op_sel_hi:[1,1,0]
	v_fma_mix_f32 v104, v89, v38, 0 op_sel:[1,1,0] op_sel_hi:[1,1,0]
	v_add_f32_dpp v101, v101, v101 quad_perm:[1,0,3,2] row_mask:0xf bank_mask:0xf bound_ctrl:1
	v_fma_mix_f32 v105, v89, v39, 0 op_sel:[1,0,0] op_sel_hi:[1,1,0]
	v_fma_mix_f32 v119, v89, v39, 0 op_sel:[1,1,0] op_sel_hi:[1,1,0]
	v_add_f32_dpp v101, v101, v101 quad_perm:[2,3,0,1] row_mask:0xf bank_mask:0xf bound_ctrl:1
	v_fma_mix_f32 v84, v84, v28, v103 op_sel:[0,0,0] op_sel_hi:[0,1,0]
	v_fma_mix_f32 v85, v85, v28, v104 op_sel:[0,1,0] op_sel_hi:[0,1,0]
	v_add_f32_dpp v101, v101, v101 row_half_mirror row_mask:0xf bank_mask:0xf bound_ctrl:1
	v_fma_mix_f32 v86, v86, v29, v105 op_sel:[0,0,0] op_sel_hi:[0,1,0]
	v_fma_mix_f32 v87, v87, v29, v119 op_sel:[0,1,0] op_sel_hi:[0,1,0]
	v_add_f32_dpp v101, v101, v101 row_mirror row_mask:0xf bank_mask:0xf bound_ctrl:1
	v_fma_mix_f32 v84, -v101, v36, v84 op_sel:[0,0,0] op_sel_hi:[0,1,0]
	v_fma_mix_f32 v85, -v101, v36, v85 op_sel:[0,1,0] op_sel_hi:[0,1,0]
	v_fma_mix_f32 v86, -v101, v37, v86 op_sel:[0,0,0] op_sel_hi:[0,1,0]
	v_fma_mix_f32 v87, -v101, v37, v87 op_sel:[0,1,0] op_sel_hi:[0,1,0]
	v_fma_mix_f32 v99, v84, v22, 0 op_sel:[0,0,0] op_sel_hi:[0,1,0]
	v_cndmask_b32_e64 v187, v97, v96, s[38:39]
	v_fma_mix_f32 v99, v85, v22, v99 op_sel:[0,1,0] op_sel_hi:[0,1,0]
	v_cndmask_b32_e64 v188, v96, v97, s[38:39]
	v_fma_mix_f32 v99, v86, v23, v99 op_sel:[0,0,0] op_sel_hi:[0,1,0]
	v_fma_mix_f32 v99, v87, v23, v99 op_sel:[0,1,0] op_sel_hi:[0,1,0]
	v_cndmask_b32_e64 v189, v99, v98, s[38:39]
	v_cndmask_b32_e64 v190, v98, v99, s[38:39]
	s_waitcnt lgkmcnt(0)
	v_fma_mix_f32 v98, v84, v74, 0 op_sel:[0,0,0] op_sel_hi:[0,1,0]
	v_fma_mix_f32 v98, v85, v74, v98 op_sel:[0,1,0] op_sel_hi:[0,1,0]
	v_add_f32_dpp v188, v188, v187 quad_perm:[1,0,3,2] row_mask:0xf bank_mask:0xf bound_ctrl:1
	v_add_f32_dpp v189, v190, v189 quad_perm:[1,0,3,2] row_mask:0xf bank_mask:0xf bound_ctrl:1
	v_fma_mix_f32 v98, v86, v75, v98 op_sel:[0,0,0] op_sel_hi:[0,1,0]
	v_fma_mix_f32 v98, v87, v75, v98 op_sel:[0,1,0] op_sel_hi:[0,1,0]
	v_cndmask_b32_e64 v191, v189, v188, s[40:41]
	v_cndmask_b32_e64 v192, v188, v189, s[40:41]
	v_fma_mix_f32 v100, v92, v78, 0 op_sel:[0,0,0] op_sel_hi:[1,1,0]
	v_fma_mix_f32 v101, v92, v78, 0 op_sel:[0,1,0] op_sel_hi:[1,1,0]
	v_add_f32_dpp v192, v192, v191 quad_perm:[2,3,0,1] row_mask:0xf bank_mask:0xf bound_ctrl:1
	v_add_f32_dpp v98, v98, v98 quad_perm:[1,0,3,2] row_mask:0xf bank_mask:0xf bound_ctrl:1
	v_fma_mix_f32 v102, v92, v79, 0 op_sel:[0,0,0] op_sel_hi:[1,1,0]
	v_add_f32_dpp v192, v192, v192 row_ror:4 row_mask:0xf bank_mask:0xf bound_ctrl:1
	v_fma_mix_f32 v103, v92, v79, 0 op_sel:[0,1,0] op_sel_hi:[1,1,0]
	v_add_f32_dpp v98, v98, v98 quad_perm:[2,3,0,1] row_mask:0xf bank_mask:0xf bound_ctrl:1
	v_add_f32_dpp v192, v192, v192 row_ror:8 row_mask:0xf bank_mask:0xf bound_ctrl:1
	v_cvt_f16_f32_e32 v192, v192
	global_store_short v83, v192, s[36:37]
	s_add_u32 s36, s36, s44
	s_addc_u32 s37, s37, s45
	s_cmp_gt_i32 s35, 9
	s_cbranch_scc0 .Lc_poll_A3

.Lc_ret_A4:
	ds_read_b128 v[0:3], v194 offset:32768
	ds_read_b128 v[4:7], v194 offset:30720
	ds_read_b128 v[8:11], v194 offset:30976
	ds_read_b128 v[12:15], v194 offset:31744
	ds_read_b128 v[16:19], v194 offset:32000
	ds_read_b128 v[20:23], v194 offset:33024
	ds_read_b128 v[24:27], v194 offset:31232
	ds_read_b128 v[28:31], v194 offset:31488
	ds_read_b128 v[32:35], v194 offset:32256
	ds_read_b128 v[36:39], v194 offset:32512
	ds_read_b64 v[88:89], v195 offset:33280
	v_fma_mix_f32 v84, v84, v72, v100 op_sel:[0,0,0] op_sel_hi:[0,1,0]
	v_fma_mix_f32 v85, v85, v72, v101 op_sel:[0,1,0] op_sel_hi:[0,1,0]
	v_add_f32_dpp v98, v98, v98 row_half_mirror row_mask:0xf bank_mask:0xf bound_ctrl:1
	v_fma_mix_f32 v86, v86, v73, v102 op_sel:[0,0,0] op_sel_hi:[0,1,0]
	v_fma_mix_f32 v87, v87, v73, v103 op_sel:[0,1,0] op_sel_hi:[0,1,0]
	v_add_f32_dpp v98, v98, v98 row_mirror row_mask:0xf bank_mask:0xf bound_ctrl:1
	v_fma_mix_f32 v84, -v98, v76, v84 op_sel:[0,0,0] op_sel_hi:[0,1,0]
	v_fma_mix_f32 v85, -v98, v76, v85 op_sel:[0,1,0] op_sel_hi:[0,1,0]
	v_fma_mix_f32 v86, -v98, v77, v86 op_sel:[0,0,0] op_sel_hi:[0,1,0]
	v_fma_mix_f32 v87, -v98, v77, v87 op_sel:[0,1,0] op_sel_hi:[0,1,0]
	v_fma_mix_f32 v73, v84, v66, 0 op_sel:[0,0,0] op_sel_hi:[0,1,0]
	v_fma_mix_f32 v97, v84, v56, 0 op_sel:[0,0,0] op_sel_hi:[0,1,0]
	v_fma_mix_f32 v73, v85, v66, v73 op_sel:[0,1,0] op_sel_hi:[0,1,0]
	v_fma_mix_f32 v56, v85, v56, v97 op_sel:[0,1,0] op_sel_hi:[0,1,0]
	v_fma_mix_f32 v73, v86, v67, v73 op_sel:[0,0,0] op_sel_hi:[0,1,0]
	v_fma_mix_f32 v56, v86, v57, v56 op_sel:[0,0,0] op_sel_hi:[0,1,0]
	v_fma_mix_f32 v73, v87, v67, v73 op_sel:[0,1,0] op_sel_hi:[0,1,0]
	v_fma_mix_f32 v56, v87, v57, v56 op_sel:[0,1,0] op_sel_hi:[0,1,0]
	v_fma_mix_f32 v75, v92, v70, 0 op_sel:[1,0,0] op_sel_hi:[1,1,0]
	v_fma_mix_f32 v76, v92, v70, 0 op_sel:[1,1,0] op_sel_hi:[1,1,0]
	v_add_f32_dpp v73, v73, v73 quad_perm:[1,0,3,2] row_mask:0xf bank_mask:0xf bound_ctrl:1
	v_fma_mix_f32 v77, v92, v71, 0 op_sel:[1,0,0] op_sel_hi:[1,1,0]
	v_fma_mix_f32 v78, v92, v71, 0 op_sel:[1,1,0] op_sel_hi:[1,1,0]
	v_add_f32_dpp v73, v73, v73 quad_perm:[2,3,0,1] row_mask:0xf bank_mask:0xf bound_ctrl:1
	v_fma_mix_f32 v84, v84, v64, v75 op_sel:[0,0,0] op_sel_hi:[0,1,0]
	v_fma_mix_f32 v85, v85, v64, v76 op_sel:[0,1,0] op_sel_hi:[0,1,0]
	v_add_f32_dpp v73, v73, v73 row_half_mirror row_mask:0xf bank_mask:0xf bound_ctrl:1
	v_fma_mix_f32 v86, v86, v65, v77 op_sel:[0,0,0] op_sel_hi:[0,1,0]
	v_fma_mix_f32 v87, v87, v65, v78 op_sel:[0,1,0] op_sel_hi:[0,1,0]
	v_add_f32_dpp v73, v73, v73 row_mirror row_mask:0xf bank_mask:0xf bound_ctrl:1
	v_fma_mix_f32 v84, -v73, v68, v84 op_sel:[0,0,0] op_sel_hi:[0,1,0]
	v_fma_mix_f32 v85, -v73, v68, v85 op_sel:[0,1,0] op_sel_hi:[0,1,0]
	v_fma_mix_f32 v86, -v73, v69, v86 op_sel:[0,0,0] op_sel_hi:[0,1,0]
	v_fma_mix_f32 v87, -v73, v69, v87 op_sel:[0,1,0] op_sel_hi:[0,1,0]
	v_fma_mix_f32 v64, v84, v54, 0 op_sel:[0,0,0] op_sel_hi:[0,1,0]
	v_fma_mix_f32 v57, v84, v58, 0 op_sel:[0,0,0] op_sel_hi:[0,1,0]
	v_fma_mix_f32 v64, v85, v54, v64 op_sel:[0,1,0] op_sel_hi:[0,1,0]
	v_fma_mix_f32 v57, v85, v58, v57 op_sel:[0,1,0] op_sel_hi:[0,1,0]
	v_fma_mix_f32 v64, v86, v55, v64 op_sel:[0,0,0] op_sel_hi:[0,1,0]
	v_fma_mix_f32 v57, v86, v59, v57 op_sel:[0,0,0] op_sel_hi:[0,1,0]
	v_fma_mix_f32 v64, v87, v55, v64 op_sel:[0,1,0] op_sel_hi:[0,1,0]
	v_fma_mix_f32 v57, v87, v59, v57 op_sel:[0,1,0] op_sel_hi:[0,1,0]
	v_fma_mix_f32 v66, v93, v62, 0 op_sel:[0,0,0] op_sel_hi:[1,1,0]
	v_fma_mix_f32 v67, v93, v62, 0 op_sel:[0,1,0] op_sel_hi:[1,1,0]
	v_add_f32_dpp v64, v64, v64 quad_perm:[1,0,3,2] row_mask:0xf bank_mask:0xf bound_ctrl:1
	v_fma_mix_f32 v68, v93, v63, 0 op_sel:[0,0,0] op_sel_hi:[1,1,0]
	v_fma_mix_f32 v69, v93, v63, 0 op_sel:[0,1,0] op_sel_hi:[1,1,0]
	v_add_f32_dpp v64, v64, v64 quad_perm:[2,3,0,1] row_mask:0xf bank_mask:0xf bound_ctrl:1
	v_fma_mix_f32 v84, v84, v52, v66 op_sel:[0,0,0] op_sel_hi:[0,1,0]
	v_fma_mix_f32 v85, v85, v52, v67 op_sel:[0,1,0] op_sel_hi:[0,1,0]
	v_add_f32_dpp v64, v64, v64 row_half_mirror row_mask:0xf bank_mask:0xf bound_ctrl:1
	v_fma_mix_f32 v86, v86, v53, v68 op_sel:[0,0,0] op_sel_hi:[0,1,0]
	v_fma_mix_f32 v87, v87, v53, v69 op_sel:[0,1,0] op_sel_hi:[0,1,0]
	v_add_f32_dpp v64, v64, v64 row_mirror row_mask:0xf bank_mask:0xf bound_ctrl:1
	v_fma_mix_f32 v84, -v64, v60, v84 op_sel:[0,0,0] op_sel_hi:[0,1,0]
	v_fma_mix_f32 v85, -v64, v60, v85 op_sel:[0,1,0] op_sel_hi:[0,1,0]
	v_fma_mix_f32 v86, -v64, v61, v86 op_sel:[0,0,0] op_sel_hi:[0,1,0]
	v_fma_mix_f32 v87, -v64, v61, v87 op_sel:[0,1,0] op_sel_hi:[0,1,0]
	v_fma_mix_f32 v53, v84, v46, 0 op_sel:[0,0,0] op_sel_hi:[0,1,0]
	v_fma_mix_f32 v59, v84, v40, 0 op_sel:[0,0,0] op_sel_hi:[0,1,0]
	v_fma_mix_f32 v53, v85, v46, v53 op_sel:[0,1,0] op_sel_hi:[0,1,0]
	v_fma_mix_f32 v40, v85, v40, v59 op_sel:[0,1,0] op_sel_hi:[0,1,0]
	v_fma_mix_f32 v53, v86, v47, v53 op_sel:[0,0,0] op_sel_hi:[0,1,0]
	v_fma_mix_f32 v40, v86, v41, v40 op_sel:[0,0,0] op_sel_hi:[0,1,0]
	v_fma_mix_f32 v53, v87, v47, v53 op_sel:[0,1,0] op_sel_hi:[0,1,0]
	v_fma_mix_f32 v40, v87, v41, v40 op_sel:[0,1,0] op_sel_hi:[0,1,0]
	v_fma_mix_f32 v55, v93, v50, 0 op_sel:[1,0,0] op_sel_hi:[1,1,0]
	v_fma_mix_f32 v58, v93, v50, 0 op_sel:[1,1,0] op_sel_hi:[1,1,0]
	v_add_f32_dpp v53, v53, v53 quad_perm:[1,0,3,2] row_mask:0xf bank_mask:0xf bound_ctrl:1
	v_fma_mix_f32 v59, v93, v51, 0 op_sel:[1,0,0] op_sel_hi:[1,1,0]
	v_fma_mix_f32 v60, v93, v51, 0 op_sel:[1,1,0] op_sel_hi:[1,1,0]
	v_add_f32_dpp v53, v53, v53 quad_perm:[2,3,0,1] row_mask:0xf bank_mask:0xf bound_ctrl:1
	v_fma_mix_f32 v84, v84, v44, v55 op_sel:[0,0,0] op_sel_hi:[0,1,0]
	v_fma_mix_f32 v85, v85, v44, v58 op_sel:[0,1,0] op_sel_hi:[0,1,0]
	v_add_f32_dpp v53, v53, v53 row_half_mirror row_mask:0xf bank_mask:0xf bound_ctrl:1
	v_fma_mix_f32 v86, v86, v45, v59 op_sel:[0,0,0] op_sel_hi:[0,1,0]
	v_fma_mix_f32 v87, v87, v45, v60 op_sel:[0,1,0] op_sel_hi:[0,1,0]
	v_add_f32_dpp v53, v53, v53 row_mirror row_mask:0xf bank_mask:0xf bound_ctrl:1
	v_fma_mix_f32 v84, -v53, v48, v84 op_sel:[0,0,0] op_sel_hi:[0,1,0]
	v_fma_mix_f32 v85, -v53, v48, v85 op_sel:[0,1,0] op_sel_hi:[0,1,0]
	v_fma_mix_f32 v86, -v53, v49, v86 op_sel:[0,0,0] op_sel_hi:[0,1,0]
	v_fma_mix_f32 v87, -v53, v49, v87 op_sel:[0,1,0] op_sel_hi:[0,1,0]
	v_fma_mix_f32 v41, v84, v42, 0 op_sel:[0,0,0] op_sel_hi:[0,1,0]
	v_cndmask_b32_e64 v187, v57, v56, s[38:39]
	v_fma_mix_f32 v41, v85, v42, v41 op_sel:[0,1,0] op_sel_hi:[0,1,0]
	v_cndmask_b32_e64 v188, v56, v57, s[38:39]
	v_fma_mix_f32 v41, v86, v43, v41 op_sel:[0,0,0] op_sel_hi:[0,1,0]
	v_fma_mix_f32 v41, v87, v43, v41 op_sel:[0,1,0] op_sel_hi:[0,1,0]
	v_cndmask_b32_e64 v189, v41, v40, s[38:39]
	v_cndmask_b32_e64 v190, v40, v41, s[38:39]
	s_waitcnt lgkmcnt(0)
	v_fma_mix_f32 v98, v84, v6, 0 op_sel:[0,0,0] op_sel_hi:[0,1,0]
	v_fma_mix_f32 v98, v85, v6, v98 op_sel:[0,1,0] op_sel_hi:[0,1,0]
	v_add_f32_dpp v188, v188, v187 quad_perm:[1,0,3,2] row_mask:0xf bank_mask:0xf bound_ctrl:1
	v_add_f32_dpp v189, v190, v189 quad_perm:[1,0,3,2] row_mask:0xf bank_mask:0xf bound_ctrl:1
	v_fma_mix_f32 v98, v86, v7, v98 op_sel:[0,0,0] op_sel_hi:[0,1,0]
	v_fma_mix_f32 v98, v87, v7, v98 op_sel:[0,1,0] op_sel_hi:[0,1,0]
	v_cndmask_b32_e64 v191, v189, v188, s[40:41]
	v_cndmask_b32_e64 v192, v188, v189, s[40:41]
	v_fma_mix_f32 v100, v88, v14, 0 op_sel:[0,0,0] op_sel_hi:[1,1,0]
	v_fma_mix_f32 v101, v88, v14, 0 op_sel:[0,1,0] op_sel_hi:[1,1,0]
	v_add_f32_dpp v192, v192, v191 quad_perm:[2,3,0,1] row_mask:0xf bank_mask:0xf bound_ctrl:1
	v_add_f32_dpp v98, v98, v98 quad_perm:[1,0,3,2] row_mask:0xf bank_mask:0xf bound_ctrl:1
	v_fma_mix_f32 v102, v88, v15, 0 op_sel:[0,0,0] op_sel_hi:[1,1,0]
	v_add_f32_dpp v192, v192, v192 row_ror:4 row_mask:0xf bank_mask:0xf bound_ctrl:1
	v_fma_mix_f32 v103, v88, v15, 0 op_sel:[0,1,0] op_sel_hi:[1,1,0]
	v_add_f32_dpp v98, v98, v98 quad_perm:[2,3,0,1] row_mask:0xf bank_mask:0xf bound_ctrl:1
	v_add_f32_dpp v192, v192, v192 row_ror:8 row_mask:0xf bank_mask:0xf bound_ctrl:1
	v_cvt_f16_f32_e32 v192, v192
	global_store_short v83, v192, s[36:37]
	s_add_u32 s36, s36, s44
	s_addc_u32 s37, s37, s45
	ds_read_b128 v[56:59], v194 offset:35840
	ds_read_b128 v[72:75], v194 offset:33792
	ds_read_b128 v[64:67], v194 offset:34048
	ds_read_b128 v[76:79], v194 offset:34816
	ds_read_b128 v[68:71], v194 offset:35072
	ds_read_b128 v[40:43], v194 offset:36096
	ds_read_b128 v[52:55], v194 offset:34304
	ds_read_b128 v[44:47], v194 offset:34560
	ds_read_b128 v[60:63], v194 offset:35328
	ds_read_b128 v[48:51], v194 offset:35584
	ds_read_b64 v[92:93], v195 offset:36352
	v_fma_mix_f32 v84, v84, v4, v100 op_sel:[0,0,0] op_sel_hi:[0,1,0]
	v_fma_mix_f32 v85, v85, v4, v101 op_sel:[0,1,0] op_sel_hi:[0,1,0]
	v_add_f32_dpp v98, v98, v98 row_half_mirror row_mask:0xf bank_mask:0xf bound_ctrl:1
	v_fma_mix_f32 v86, v86, v5, v102 op_sel:[0,0,0] op_sel_hi:[0,1,0]
	v_fma_mix_f32 v87, v87, v5, v103 op_sel:[0,1,0] op_sel_hi:[0,1,0]
	v_add_f32_dpp v98, v98, v98 row_mirror row_mask:0xf bank_mask:0xf bound_ctrl:1
	v_fma_mix_f32 v84, -v98, v12, v84 op_sel:[0,0,0] op_sel_hi:[0,1,0]
	v_fma_mix_f32 v85, -v98, v12, v85 op_sel:[0,1,0] op_sel_hi:[0,1,0]
	v_fma_mix_f32 v86, -v98, v13, v86 op_sel:[0,0,0] op_sel_hi:[0,1,0]
	v_fma_mix_f32 v87, -v98, v13, v87 op_sel:[0,1,0] op_sel_hi:[0,1,0]
	v_fma_mix_f32 v99, v84, v10, 0 op_sel:[0,0,0] op_sel_hi:[0,1,0]
	v_fma_mix_f32 v96, v84, v0, 0 op_sel:[0,0,0] op_sel_hi:[0,1,0]
	v_fma_mix_f32 v99, v85, v10, v99 op_sel:[0,1,0] op_sel_hi:[0,1,0]
	v_fma_mix_f32 v96, v85, v0, v96 op_sel:[0,1,0] op_sel_hi:[0,1,0]
	v_fma_mix_f32 v99, v86, v11, v99 op_sel:[0,0,0] op_sel_hi:[0,1,0]
	v_fma_mix_f32 v96, v86, v1, v96 op_sel:[0,0,0] op_sel_hi:[0,1,0]
	v_fma_mix_f32 v99, v87, v11, v99 op_sel:[0,1,0] op_sel_hi:[0,1,0]
	v_fma_mix_f32 v96, v87, v1, v96 op_sel:[0,1,0] op_sel_hi:[0,1,0]
	v_fma_mix_f32 v101, v88, v18, 0 op_sel:[1,0,0] op_sel_hi:[1,1,0]
	v_fma_mix_f32 v102, v88, v18, 0 op_sel:[1,1,0] op_sel_hi:[1,1,0]
	v_add_f32_dpp v99, v99, v99 quad_perm:[1,0,3,2] row_mask:0xf bank_mask:0xf bound_ctrl:1
	v_fma_mix_f32 v103, v88, v19, 0 op_sel:[1,0,0] op_sel_hi:[1,1,0]
	v_fma_mix_f32 v104, v88, v19, 0 op_sel:[1,1,0] op_sel_hi:[1,1,0]
	v_add_f32_dpp v99, v99, v99 quad_perm:[2,3,0,1] row_mask:0xf bank_mask:0xf bound_ctrl:1
	v_fma_mix_f32 v84, v84, v8, v101 op_sel:[0,0,0] op_sel_hi:[0,1,0]
	v_fma_mix_f32 v85, v85, v8, v102 op_sel:[0,1,0] op_sel_hi:[0,1,0]
	v_add_f32_dpp v99, v99, v99 row_half_mirror row_mask:0xf bank_mask:0xf bound_ctrl:1
	v_fma_mix_f32 v86, v86, v9, v103 op_sel:[0,0,0] op_sel_hi:[0,1,0]
	v_fma_mix_f32 v87, v87, v9, v104 op_sel:[0,1,0] op_sel_hi:[0,1,0]
	v_add_f32_dpp v99, v99, v99 row_mirror row_mask:0xf bank_mask:0xf bound_ctrl:1
	v_fma_mix_f32 v84, -v99, v16, v84 op_sel:[0,0,0] op_sel_hi:[0,1,0]
	v_fma_mix_f32 v85, -v99, v16, v85 op_sel:[0,1,0] op_sel_hi:[0,1,0]
	v_fma_mix_f32 v86, -v99, v17, v86 op_sel:[0,0,0] op_sel_hi:[0,1,0]
	v_fma_mix_f32 v87, -v99, v17, v87 op_sel:[0,1,0] op_sel_hi:[0,1,0]
	v_fma_mix_f32 v100, v84, v26, 0 op_sel:[0,0,0] op_sel_hi:[0,1,0]
	v_fma_mix_f32 v97, v84, v2, 0 op_sel:[0,0,0] op_sel_hi:[0,1,0]
	v_fma_mix_f32 v100, v85, v26, v100 op_sel:[0,1,0] op_sel_hi:[0,1,0]
	v_fma_mix_f32 v97, v85, v2, v97 op_sel:[0,1,0] op_sel_hi:[0,1,0]
	v_fma_mix_f32 v100, v86, v27, v100 op_sel:[0,0,0] op_sel_hi:[0,1,0]
	v_fma_mix_f32 v97, v86, v3, v97 op_sel:[0,0,0] op_sel_hi:[0,1,0]
	v_fma_mix_f32 v100, v87, v27, v100 op_sel:[0,1,0] op_sel_hi:[0,1,0]
	v_fma_mix_f32 v97, v87, v3, v97 op_sel:[0,1,0] op_sel_hi:[0,1,0]
	v_fma_mix_f32 v102, v89, v34, 0 op_sel:[0,0,0] op_sel_hi:[1,1,0]
	v_fma_mix_f32 v103, v89, v34, 0 op_sel:[0,1,0] op_sel_hi:[1,1,0]
	v_add_f32_dpp v100, v100, v100 quad_perm:[1,0,3,2] row_mask:0xf bank_mask:0xf bound_ctrl:1
	v_fma_mix_f32 v104, v89, v35, 0 op_sel:[0,0,0] op_sel_hi:[1,1,0]
	v_fma_mix_f32 v105, v89, v35, 0 op_sel:[0,1,0] op_sel_hi:[1,1,0]
	v_add_f32_dpp v100, v100, v100 quad_perm:[2,3,0,1] row_mask:0xf bank_mask:0xf bound_ctrl:1
	v_fma_mix_f32 v84, v84, v24, v102 op_sel:[0,0,0] op_sel_hi:[0,1,0]
	v_fma_mix_f32 v85, v85, v24, v103 op_sel:[0,1,0] op_sel_hi:[0,1,0]
	v_add_f32_dpp v100, v100, v100 row_half_mirror row_mask:0xf bank_mask:0xf bound_ctrl:1
	v_fma_mix_f32 v86, v86, v25, v104 op_sel:[0,0,0] op_sel_hi:[0,1,0]
	v_fma_mix_f32 v87, v87, v25, v105 op_sel:[0,1,0] op_sel_hi:[0,1,0]
	v_add_f32_dpp v100, v100, v100 row_mirror row_mask:0xf bank_mask:0xf bound_ctrl:1
	v_fma_mix_f32 v84, -v100, v32, v84 op_sel:[0,0,0] op_sel_hi:[0,1,0]
	v_fma_mix_f32 v85, -v100, v32, v85 op_sel:[0,1,0] op_sel_hi:[0,1,0]
	v_fma_mix_f32 v86, -v100, v33, v86 op_sel:[0,0,0] op_sel_hi:[0,1,0]
	v_fma_mix_f32 v87, -v100, v33, v87 op_sel:[0,1,0] op_sel_hi:[0,1,0]
	v_fma_mix_f32 v101, v84, v30, 0 op_sel:[0,0,0] op_sel_hi:[0,1,0]
	v_fma_mix_f32 v98, v84, v20, 0 op_sel:[0,0,0] op_sel_hi:[0,1,0]
	v_fma_mix_f32 v101, v85, v30, v101 op_sel:[0,1,0] op_sel_hi:[0,1,0]
	v_fma_mix_f32 v98, v85, v20, v98 op_sel:[0,1,0] op_sel_hi:[0,1,0]
	v_fma_mix_f32 v101, v86, v31, v101 op_sel:[0,0,0] op_sel_hi:[0,1,0]
	v_fma_mix_f32 v98, v86, v21, v98 op_sel:[0,0,0] op_sel_hi:[0,1,0]
	v_fma_mix_f32 v101, v87, v31, v101 op_sel:[0,1,0] op_sel_hi:[0,1,0]
	v_fma_mix_f32 v98, v87, v21, v98 op_sel:[0,1,0] op_sel_hi:[0,1,0]
	v_fma_mix_f32 v103, v89, v38, 0 op_sel:[1,0,0] op_sel_hi:[1,1,0]
	v_fma_mix_f32 v104, v89, v38, 0 op_sel:[1,1,0] op_sel_hi:[1,1,0]
	v_add_f32_dpp v101, v101, v101 quad_perm:[1,0,3,2] row_mask:0xf bank_mask:0xf bound_ctrl:1
	v_fma_mix_f32 v105, v89, v39, 0 op_sel:[1,0,0] op_sel_hi:[1,1,0]
	v_fma_mix_f32 v119, v89, v39, 0 op_sel:[1,1,0] op_sel_hi:[1,1,0]
	v_add_f32_dpp v101, v101, v101 quad_perm:[2,3,0,1] row_mask:0xf bank_mask:0xf bound_ctrl:1
	v_fma_mix_f32 v84, v84, v28, v103 op_sel:[0,0,0] op_sel_hi:[0,1,0]
	v_fma_mix_f32 v85, v85, v28, v104 op_sel:[0,1,0] op_sel_hi:[0,1,0]
	v_add_f32_dpp v101, v101, v101 row_half_mirror row_mask:0xf bank_mask:0xf bound_ctrl:1
	v_fma_mix_f32 v86, v86, v29, v105 op_sel:[0,0,0] op_sel_hi:[0,1,0]
	v_fma_mix_f32 v87, v87, v29, v119 op_sel:[0,1,0] op_sel_hi:[0,1,0]
	v_add_f32_dpp v101, v101, v101 row_mirror row_mask:0xf bank_mask:0xf bound_ctrl:1
	v_fma_mix_f32 v84, -v101, v36, v84 op_sel:[0,0,0] op_sel_hi:[0,1,0]
	v_fma_mix_f32 v85, -v101, v36, v85 op_sel:[0,1,0] op_sel_hi:[0,1,0]
	v_fma_mix_f32 v86, -v101, v37, v86 op_sel:[0,0,0] op_sel_hi:[0,1,0]
	v_fma_mix_f32 v87, -v101, v37, v87 op_sel:[0,1,0] op_sel_hi:[0,1,0]
	v_fma_mix_f32 v99, v84, v22, 0 op_sel:[0,0,0] op_sel_hi:[0,1,0]
	v_cndmask_b32_e64 v187, v97, v96, s[38:39]
	v_fma_mix_f32 v99, v85, v22, v99 op_sel:[0,1,0] op_sel_hi:[0,1,0]
	v_cndmask_b32_e64 v188, v96, v97, s[38:39]
	v_fma_mix_f32 v99, v86, v23, v99 op_sel:[0,0,0] op_sel_hi:[0,1,0]
	v_fma_mix_f32 v99, v87, v23, v99 op_sel:[0,1,0] op_sel_hi:[0,1,0]
	v_cndmask_b32_e64 v189, v99, v98, s[38:39]
	v_cndmask_b32_e64 v190, v98, v99, s[38:39]
	s_waitcnt lgkmcnt(0)
	v_fma_mix_f32 v98, v84, v74, 0 op_sel:[0,0,0] op_sel_hi:[0,1,0]
	v_fma_mix_f32 v98, v85, v74, v98 op_sel:[0,1,0] op_sel_hi:[0,1,0]
	v_add_f32_dpp v188, v188, v187 quad_perm:[1,0,3,2] row_mask:0xf bank_mask:0xf bound_ctrl:1
	v_add_f32_dpp v189, v190, v189 quad_perm:[1,0,3,2] row_mask:0xf bank_mask:0xf bound_ctrl:1
	v_fma_mix_f32 v98, v86, v75, v98 op_sel:[0,0,0] op_sel_hi:[0,1,0]
	v_fma_mix_f32 v98, v87, v75, v98 op_sel:[0,1,0] op_sel_hi:[0,1,0]
	v_cndmask_b32_e64 v191, v189, v188, s[40:41]
	v_cndmask_b32_e64 v192, v188, v189, s[40:41]
	v_fma_mix_f32 v100, v92, v78, 0 op_sel:[0,0,0] op_sel_hi:[1,1,0]
	v_fma_mix_f32 v101, v92, v78, 0 op_sel:[0,1,0] op_sel_hi:[1,1,0]
	v_add_f32_dpp v192, v192, v191 quad_perm:[2,3,0,1] row_mask:0xf bank_mask:0xf bound_ctrl:1
	v_add_f32_dpp v98, v98, v98 quad_perm:[1,0,3,2] row_mask:0xf bank_mask:0xf bound_ctrl:1
	v_fma_mix_f32 v102, v92, v79, 0 op_sel:[0,0,0] op_sel_hi:[1,1,0]
	v_add_f32_dpp v192, v192, v192 row_ror:4 row_mask:0xf bank_mask:0xf bound_ctrl:1
	v_fma_mix_f32 v103, v92, v79, 0 op_sel:[0,1,0] op_sel_hi:[1,1,0]
	v_add_f32_dpp v98, v98, v98 quad_perm:[2,3,0,1] row_mask:0xf bank_mask:0xf bound_ctrl:1
	v_add_f32_dpp v192, v192, v192 row_ror:8 row_mask:0xf bank_mask:0xf bound_ctrl:1
	v_cvt_f16_f32_e32 v192, v192
	global_store_short v83, v192, s[36:37]
	s_add_u32 s36, s36, s44
	s_addc_u32 s37, s37, s45
	s_cmp_gt_i32 s35, 13
	s_cbranch_scc0 .Lc_poll_A5

.Lc_ret_A6:
	ds_read_b128 v[0:3], v194 offset:45056
	ds_read_b128 v[4:7], v194 offset:43008
	ds_read_b128 v[8:11], v194 offset:43264
	ds_read_b128 v[12:15], v194 offset:44032
	ds_read_b128 v[16:19], v194 offset:44288
	ds_read_b128 v[20:23], v194 offset:45312
	ds_read_b128 v[24:27], v194 offset:43520
	ds_read_b128 v[28:31], v194 offset:43776
	ds_read_b128 v[32:35], v194 offset:44544
	ds_read_b128 v[36:39], v194 offset:44800
	ds_read_b64 v[88:89], v195 offset:45568
	v_fma_mix_f32 v84, v84, v72, v100 op_sel:[0,0,0] op_sel_hi:[0,1,0]
	v_fma_mix_f32 v85, v85, v72, v101 op_sel:[0,1,0] op_sel_hi:[0,1,0]
	v_add_f32_dpp v98, v98, v98 row_half_mirror row_mask:0xf bank_mask:0xf bound_ctrl:1
	v_fma_mix_f32 v86, v86, v73, v102 op_sel:[0,0,0] op_sel_hi:[0,1,0]
	v_fma_mix_f32 v87, v87, v73, v103 op_sel:[0,1,0] op_sel_hi:[0,1,0]
	v_add_f32_dpp v98, v98, v98 row_mirror row_mask:0xf bank_mask:0xf bound_ctrl:1
	v_fma_mix_f32 v84, -v98, v76, v84 op_sel:[0,0,0] op_sel_hi:[0,1,0]
	v_fma_mix_f32 v85, -v98, v76, v85 op_sel:[0,1,0] op_sel_hi:[0,1,0]
	v_fma_mix_f32 v86, -v98, v77, v86 op_sel:[0,0,0] op_sel_hi:[0,1,0]
	v_fma_mix_f32 v87, -v98, v77, v87 op_sel:[0,1,0] op_sel_hi:[0,1,0]
	v_fma_mix_f32 v73, v84, v66, 0 op_sel:[0,0,0] op_sel_hi:[0,1,0]
	v_fma_mix_f32 v97, v84, v56, 0 op_sel:[0,0,0] op_sel_hi:[0,1,0]
	v_fma_mix_f32 v73, v85, v66, v73 op_sel:[0,1,0] op_sel_hi:[0,1,0]
	v_fma_mix_f32 v56, v85, v56, v97 op_sel:[0,1,0] op_sel_hi:[0,1,0]
	v_fma_mix_f32 v73, v86, v67, v73 op_sel:[0,0,0] op_sel_hi:[0,1,0]
	v_fma_mix_f32 v56, v86, v57, v56 op_sel:[0,0,0] op_sel_hi:[0,1,0]
	v_fma_mix_f32 v73, v87, v67, v73 op_sel:[0,1,0] op_sel_hi:[0,1,0]
	v_fma_mix_f32 v56, v87, v57, v56 op_sel:[0,1,0] op_sel_hi:[0,1,0]
	v_fma_mix_f32 v75, v92, v70, 0 op_sel:[1,0,0] op_sel_hi:[1,1,0]
	v_fma_mix_f32 v76, v92, v70, 0 op_sel:[1,1,0] op_sel_hi:[1,1,0]
	v_add_f32_dpp v73, v73, v73 quad_perm:[1,0,3,2] row_mask:0xf bank_mask:0xf bound_ctrl:1
	v_fma_mix_f32 v77, v92, v71, 0 op_sel:[1,0,0] op_sel_hi:[1,1,0]
	v_fma_mix_f32 v78, v92, v71, 0 op_sel:[1,1,0] op_sel_hi:[1,1,0]
	v_add_f32_dpp v73, v73, v73 quad_perm:[2,3,0,1] row_mask:0xf bank_mask:0xf bound_ctrl:1
	v_fma_mix_f32 v84, v84, v64, v75 op_sel:[0,0,0] op_sel_hi:[0,1,0]
	v_fma_mix_f32 v85, v85, v64, v76 op_sel:[0,1,0] op_sel_hi:[0,1,0]
	v_add_f32_dpp v73, v73, v73 row_half_mirror row_mask:0xf bank_mask:0xf bound_ctrl:1
	v_fma_mix_f32 v86, v86, v65, v77 op_sel:[0,0,0] op_sel_hi:[0,1,0]
	v_fma_mix_f32 v87, v87, v65, v78 op_sel:[0,1,0] op_sel_hi:[0,1,0]
	v_add_f32_dpp v73, v73, v73 row_mirror row_mask:0xf bank_mask:0xf bound_ctrl:1
	v_fma_mix_f32 v84, -v73, v68, v84 op_sel:[0,0,0] op_sel_hi:[0,1,0]
	v_fma_mix_f32 v85, -v73, v68, v85 op_sel:[0,1,0] op_sel_hi:[0,1,0]
	v_fma_mix_f32 v86, -v73, v69, v86 op_sel:[0,0,0] op_sel_hi:[0,1,0]
	v_fma_mix_f32 v87, -v73, v69, v87 op_sel:[0,1,0] op_sel_hi:[0,1,0]
	v_fma_mix_f32 v64, v84, v54, 0 op_sel:[0,0,0] op_sel_hi:[0,1,0]
	v_fma_mix_f32 v57, v84, v58, 0 op_sel:[0,0,0] op_sel_hi:[0,1,0]
	v_fma_mix_f32 v64, v85, v54, v64 op_sel:[0,1,0] op_sel_hi:[0,1,0]
	v_fma_mix_f32 v57, v85, v58, v57 op_sel:[0,1,0] op_sel_hi:[0,1,0]
	v_fma_mix_f32 v64, v86, v55, v64 op_sel:[0,0,0] op_sel_hi:[0,1,0]
	v_fma_mix_f32 v57, v86, v59, v57 op_sel:[0,0,0] op_sel_hi:[0,1,0]
	v_fma_mix_f32 v64, v87, v55, v64 op_sel:[0,1,0] op_sel_hi:[0,1,0]
	v_fma_mix_f32 v57, v87, v59, v57 op_sel:[0,1,0] op_sel_hi:[0,1,0]
	v_fma_mix_f32 v66, v93, v62, 0 op_sel:[0,0,0] op_sel_hi:[1,1,0]
	v_fma_mix_f32 v67, v93, v62, 0 op_sel:[0,1,0] op_sel_hi:[1,1,0]
	v_add_f32_dpp v64, v64, v64 quad_perm:[1,0,3,2] row_mask:0xf bank_mask:0xf bound_ctrl:1
	v_fma_mix_f32 v68, v93, v63, 0 op_sel:[0,0,0] op_sel_hi:[1,1,0]
	v_fma_mix_f32 v69, v93, v63, 0 op_sel:[0,1,0] op_sel_hi:[1,1,0]
	v_add_f32_dpp v64, v64, v64 quad_perm:[2,3,0,1] row_mask:0xf bank_mask:0xf bound_ctrl:1
	v_fma_mix_f32 v84, v84, v52, v66 op_sel:[0,0,0] op_sel_hi:[0,1,0]
	v_fma_mix_f32 v85, v85, v52, v67 op_sel:[0,1,0] op_sel_hi:[0,1,0]
	v_add_f32_dpp v64, v64, v64 row_half_mirror row_mask:0xf bank_mask:0xf bound_ctrl:1
	v_fma_mix_f32 v86, v86, v53, v68 op_sel:[0,0,0] op_sel_hi:[0,1,0]
	v_fma_mix_f32 v87, v87, v53, v69 op_sel:[0,1,0] op_sel_hi:[0,1,0]
	v_add_f32_dpp v64, v64, v64 row_mirror row_mask:0xf bank_mask:0xf bound_ctrl:1
	v_fma_mix_f32 v84, -v64, v60, v84 op_sel:[0,0,0] op_sel_hi:[0,1,0]
	v_fma_mix_f32 v85, -v64, v60, v85 op_sel:[0,1,0] op_sel_hi:[0,1,0]
	v_fma_mix_f32 v86, -v64, v61, v86 op_sel:[0,0,0] op_sel_hi:[0,1,0]
	v_fma_mix_f32 v87, -v64, v61, v87 op_sel:[0,1,0] op_sel_hi:[0,1,0]
	v_fma_mix_f32 v53, v84, v46, 0 op_sel:[0,0,0] op_sel_hi:[0,1,0]
	v_fma_mix_f32 v59, v84, v40, 0 op_sel:[0,0,0] op_sel_hi:[0,1,0]
	v_fma_mix_f32 v53, v85, v46, v53 op_sel:[0,1,0] op_sel_hi:[0,1,0]
	v_fma_mix_f32 v40, v85, v40, v59 op_sel:[0,1,0] op_sel_hi:[0,1,0]
	v_fma_mix_f32 v53, v86, v47, v53 op_sel:[0,0,0] op_sel_hi:[0,1,0]
	v_fma_mix_f32 v40, v86, v41, v40 op_sel:[0,0,0] op_sel_hi:[0,1,0]
	v_fma_mix_f32 v53, v87, v47, v53 op_sel:[0,1,0] op_sel_hi:[0,1,0]
	v_fma_mix_f32 v40, v87, v41, v40 op_sel:[0,1,0] op_sel_hi:[0,1,0]
	v_fma_mix_f32 v55, v93, v50, 0 op_sel:[1,0,0] op_sel_hi:[1,1,0]
	v_fma_mix_f32 v58, v93, v50, 0 op_sel:[1,1,0] op_sel_hi:[1,1,0]
	v_add_f32_dpp v53, v53, v53 quad_perm:[1,0,3,2] row_mask:0xf bank_mask:0xf bound_ctrl:1
	v_fma_mix_f32 v59, v93, v51, 0 op_sel:[1,0,0] op_sel_hi:[1,1,0]
	v_fma_mix_f32 v60, v93, v51, 0 op_sel:[1,1,0] op_sel_hi:[1,1,0]
	v_add_f32_dpp v53, v53, v53 quad_perm:[2,3,0,1] row_mask:0xf bank_mask:0xf bound_ctrl:1
	v_fma_mix_f32 v84, v84, v44, v55 op_sel:[0,0,0] op_sel_hi:[0,1,0]
	v_fma_mix_f32 v85, v85, v44, v58 op_sel:[0,1,0] op_sel_hi:[0,1,0]
	v_add_f32_dpp v53, v53, v53 row_half_mirror row_mask:0xf bank_mask:0xf bound_ctrl:1
	v_fma_mix_f32 v86, v86, v45, v59 op_sel:[0,0,0] op_sel_hi:[0,1,0]
	v_fma_mix_f32 v87, v87, v45, v60 op_sel:[0,1,0] op_sel_hi:[0,1,0]
	v_add_f32_dpp v53, v53, v53 row_mirror row_mask:0xf bank_mask:0xf bound_ctrl:1
	v_fma_mix_f32 v84, -v53, v48, v84 op_sel:[0,0,0] op_sel_hi:[0,1,0]
	v_fma_mix_f32 v85, -v53, v48, v85 op_sel:[0,1,0] op_sel_hi:[0,1,0]
	v_fma_mix_f32 v86, -v53, v49, v86 op_sel:[0,0,0] op_sel_hi:[0,1,0]
	v_fma_mix_f32 v87, -v53, v49, v87 op_sel:[0,1,0] op_sel_hi:[0,1,0]
	v_fma_mix_f32 v41, v84, v42, 0 op_sel:[0,0,0] op_sel_hi:[0,1,0]
	v_cndmask_b32_e64 v187, v57, v56, s[38:39]
	v_fma_mix_f32 v41, v85, v42, v41 op_sel:[0,1,0] op_sel_hi:[0,1,0]
	v_cndmask_b32_e64 v188, v56, v57, s[38:39]
	v_fma_mix_f32 v41, v86, v43, v41 op_sel:[0,0,0] op_sel_hi:[0,1,0]
	v_fma_mix_f32 v41, v87, v43, v41 op_sel:[0,1,0] op_sel_hi:[0,1,0]
	v_cndmask_b32_e64 v189, v41, v40, s[38:39]
	v_cndmask_b32_e64 v190, v40, v41, s[38:39]
	s_waitcnt lgkmcnt(0)
	v_fma_mix_f32 v98, v84, v6, 0 op_sel:[0,0,0] op_sel_hi:[0,1,0]
	v_fma_mix_f32 v98, v85, v6, v98 op_sel:[0,1,0] op_sel_hi:[0,1,0]
	v_add_f32_dpp v188, v188, v187 quad_perm:[1,0,3,2] row_mask:0xf bank_mask:0xf bound_ctrl:1
	v_add_f32_dpp v189, v190, v189 quad_perm:[1,0,3,2] row_mask:0xf bank_mask:0xf bound_ctrl:1
	v_fma_mix_f32 v98, v86, v7, v98 op_sel:[0,0,0] op_sel_hi:[0,1,0]
	v_fma_mix_f32 v98, v87, v7, v98 op_sel:[0,1,0] op_sel_hi:[0,1,0]
	v_cndmask_b32_e64 v191, v189, v188, s[40:41]
	v_cndmask_b32_e64 v192, v188, v189, s[40:41]
	v_fma_mix_f32 v100, v88, v14, 0 op_sel:[0,0,0] op_sel_hi:[1,1,0]
	v_fma_mix_f32 v101, v88, v14, 0 op_sel:[0,1,0] op_sel_hi:[1,1,0]
	v_add_f32_dpp v192, v192, v191 quad_perm:[2,3,0,1] row_mask:0xf bank_mask:0xf bound_ctrl:1
	v_add_f32_dpp v98, v98, v98 quad_perm:[1,0,3,2] row_mask:0xf bank_mask:0xf bound_ctrl:1
	v_fma_mix_f32 v102, v88, v15, 0 op_sel:[0,0,0] op_sel_hi:[1,1,0]
	v_add_f32_dpp v192, v192, v192 row_ror:4 row_mask:0xf bank_mask:0xf bound_ctrl:1
	v_fma_mix_f32 v103, v88, v15, 0 op_sel:[0,1,0] op_sel_hi:[1,1,0]
	v_add_f32_dpp v98, v98, v98 quad_perm:[2,3,0,1] row_mask:0xf bank_mask:0xf bound_ctrl:1
	v_add_f32_dpp v192, v192, v192 row_ror:8 row_mask:0xf bank_mask:0xf bound_ctrl:1
	v_cvt_f16_f32_e32 v192, v192
	global_store_short v83, v192, s[36:37]
	s_add_u32 s36, s36, s44
	s_addc_u32 s37, s37, s45
	ds_read_b128 v[56:59], v194 offset:48128
	ds_read_b128 v[72:75], v194 offset:46080
	ds_read_b128 v[64:67], v194 offset:46336
	ds_read_b128 v[76:79], v194 offset:47104
	ds_read_b128 v[68:71], v194 offset:47360
	ds_read_b128 v[40:43], v194 offset:48384
	ds_read_b128 v[52:55], v194 offset:46592
	ds_read_b128 v[44:47], v194 offset:46848
	ds_read_b128 v[60:63], v194 offset:47616
	ds_read_b128 v[48:51], v194 offset:47872
	ds_read_b64 v[92:93], v195 offset:48640
	v_fma_mix_f32 v84, v84, v4, v100 op_sel:[0,0,0] op_sel_hi:[0,1,0]
	v_fma_mix_f32 v85, v85, v4, v101 op_sel:[0,1,0] op_sel_hi:[0,1,0]
	v_add_f32_dpp v98, v98, v98 row_half_mirror row_mask:0xf bank_mask:0xf bound_ctrl:1
	v_fma_mix_f32 v86, v86, v5, v102 op_sel:[0,0,0] op_sel_hi:[0,1,0]
	v_fma_mix_f32 v87, v87, v5, v103 op_sel:[0,1,0] op_sel_hi:[0,1,0]
	v_add_f32_dpp v98, v98, v98 row_mirror row_mask:0xf bank_mask:0xf bound_ctrl:1
	v_fma_mix_f32 v84, -v98, v12, v84 op_sel:[0,0,0] op_sel_hi:[0,1,0]
	v_fma_mix_f32 v85, -v98, v12, v85 op_sel:[0,1,0] op_sel_hi:[0,1,0]
	v_fma_mix_f32 v86, -v98, v13, v86 op_sel:[0,0,0] op_sel_hi:[0,1,0]
	v_fma_mix_f32 v87, -v98, v13, v87 op_sel:[0,1,0] op_sel_hi:[0,1,0]
	v_fma_mix_f32 v99, v84, v10, 0 op_sel:[0,0,0] op_sel_hi:[0,1,0]
	v_fma_mix_f32 v96, v84, v0, 0 op_sel:[0,0,0] op_sel_hi:[0,1,0]
	v_fma_mix_f32 v99, v85, v10, v99 op_sel:[0,1,0] op_sel_hi:[0,1,0]
	v_fma_mix_f32 v96, v85, v0, v96 op_sel:[0,1,0] op_sel_hi:[0,1,0]
	v_fma_mix_f32 v99, v86, v11, v99 op_sel:[0,0,0] op_sel_hi:[0,1,0]
	v_fma_mix_f32 v96, v86, v1, v96 op_sel:[0,0,0] op_sel_hi:[0,1,0]
	v_fma_mix_f32 v99, v87, v11, v99 op_sel:[0,1,0] op_sel_hi:[0,1,0]
	v_fma_mix_f32 v96, v87, v1, v96 op_sel:[0,1,0] op_sel_hi:[0,1,0]
	v_fma_mix_f32 v101, v88, v18, 0 op_sel:[1,0,0] op_sel_hi:[1,1,0]
	v_fma_mix_f32 v102, v88, v18, 0 op_sel:[1,1,0] op_sel_hi:[1,1,0]
	v_add_f32_dpp v99, v99, v99 quad_perm:[1,0,3,2] row_mask:0xf bank_mask:0xf bound_ctrl:1
	v_fma_mix_f32 v103, v88, v19, 0 op_sel:[1,0,0] op_sel_hi:[1,1,0]
	v_fma_mix_f32 v104, v88, v19, 0 op_sel:[1,1,0] op_sel_hi:[1,1,0]
	v_add_f32_dpp v99, v99, v99 quad_perm:[2,3,0,1] row_mask:0xf bank_mask:0xf bound_ctrl:1
	v_fma_mix_f32 v84, v84, v8, v101 op_sel:[0,0,0] op_sel_hi:[0,1,0]
	v_fma_mix_f32 v85, v85, v8, v102 op_sel:[0,1,0] op_sel_hi:[0,1,0]
	v_add_f32_dpp v99, v99, v99 row_half_mirror row_mask:0xf bank_mask:0xf bound_ctrl:1
	v_fma_mix_f32 v86, v86, v9, v103 op_sel:[0,0,0] op_sel_hi:[0,1,0]
	v_fma_mix_f32 v87, v87, v9, v104 op_sel:[0,1,0] op_sel_hi:[0,1,0]
	v_add_f32_dpp v99, v99, v99 row_mirror row_mask:0xf bank_mask:0xf bound_ctrl:1
	v_fma_mix_f32 v84, -v99, v16, v84 op_sel:[0,0,0] op_sel_hi:[0,1,0]
	v_fma_mix_f32 v85, -v99, v16, v85 op_sel:[0,1,0] op_sel_hi:[0,1,0]
	v_fma_mix_f32 v86, -v99, v17, v86 op_sel:[0,0,0] op_sel_hi:[0,1,0]
	v_fma_mix_f32 v87, -v99, v17, v87 op_sel:[0,1,0] op_sel_hi:[0,1,0]
	v_fma_mix_f32 v100, v84, v26, 0 op_sel:[0,0,0] op_sel_hi:[0,1,0]
	v_fma_mix_f32 v97, v84, v2, 0 op_sel:[0,0,0] op_sel_hi:[0,1,0]
	v_fma_mix_f32 v100, v85, v26, v100 op_sel:[0,1,0] op_sel_hi:[0,1,0]
	v_fma_mix_f32 v97, v85, v2, v97 op_sel:[0,1,0] op_sel_hi:[0,1,0]
	v_fma_mix_f32 v100, v86, v27, v100 op_sel:[0,0,0] op_sel_hi:[0,1,0]
	v_fma_mix_f32 v97, v86, v3, v97 op_sel:[0,0,0] op_sel_hi:[0,1,0]
	v_fma_mix_f32 v100, v87, v27, v100 op_sel:[0,1,0] op_sel_hi:[0,1,0]
	v_fma_mix_f32 v97, v87, v3, v97 op_sel:[0,1,0] op_sel_hi:[0,1,0]
	v_fma_mix_f32 v102, v89, v34, 0 op_sel:[0,0,0] op_sel_hi:[1,1,0]
	v_fma_mix_f32 v103, v89, v34, 0 op_sel:[0,1,0] op_sel_hi:[1,1,0]
	v_add_f32_dpp v100, v100, v100 quad_perm:[1,0,3,2] row_mask:0xf bank_mask:0xf bound_ctrl:1
	v_fma_mix_f32 v104, v89, v35, 0 op_sel:[0,0,0] op_sel_hi:[1,1,0]
	v_fma_mix_f32 v105, v89, v35, 0 op_sel:[0,1,0] op_sel_hi:[1,1,0]
	v_add_f32_dpp v100, v100, v100 quad_perm:[2,3,0,1] row_mask:0xf bank_mask:0xf bound_ctrl:1
	v_fma_mix_f32 v84, v84, v24, v102 op_sel:[0,0,0] op_sel_hi:[0,1,0]
	v_fma_mix_f32 v85, v85, v24, v103 op_sel:[0,1,0] op_sel_hi:[0,1,0]
	v_add_f32_dpp v100, v100, v100 row_half_mirror row_mask:0xf bank_mask:0xf bound_ctrl:1
	v_fma_mix_f32 v86, v86, v25, v104 op_sel:[0,0,0] op_sel_hi:[0,1,0]
	v_fma_mix_f32 v87, v87, v25, v105 op_sel:[0,1,0] op_sel_hi:[0,1,0]
	v_add_f32_dpp v100, v100, v100 row_mirror row_mask:0xf bank_mask:0xf bound_ctrl:1
	v_fma_mix_f32 v84, -v100, v32, v84 op_sel:[0,0,0] op_sel_hi:[0,1,0]
	v_fma_mix_f32 v85, -v100, v32, v85 op_sel:[0,1,0] op_sel_hi:[0,1,0]
	v_fma_mix_f32 v86, -v100, v33, v86 op_sel:[0,0,0] op_sel_hi:[0,1,0]
	v_fma_mix_f32 v87, -v100, v33, v87 op_sel:[0,1,0] op_sel_hi:[0,1,0]
	v_fma_mix_f32 v101, v84, v30, 0 op_sel:[0,0,0] op_sel_hi:[0,1,0]
	v_fma_mix_f32 v98, v84, v20, 0 op_sel:[0,0,0] op_sel_hi:[0,1,0]
	v_fma_mix_f32 v101, v85, v30, v101 op_sel:[0,1,0] op_sel_hi:[0,1,0]
	v_fma_mix_f32 v98, v85, v20, v98 op_sel:[0,1,0] op_sel_hi:[0,1,0]
	v_fma_mix_f32 v101, v86, v31, v101 op_sel:[0,0,0] op_sel_hi:[0,1,0]
	v_fma_mix_f32 v98, v86, v21, v98 op_sel:[0,0,0] op_sel_hi:[0,1,0]
	v_fma_mix_f32 v101, v87, v31, v101 op_sel:[0,1,0] op_sel_hi:[0,1,0]
	v_fma_mix_f32 v98, v87, v21, v98 op_sel:[0,1,0] op_sel_hi:[0,1,0]
	v_fma_mix_f32 v103, v89, v38, 0 op_sel:[1,0,0] op_sel_hi:[1,1,0]
	v_fma_mix_f32 v104, v89, v38, 0 op_sel:[1,1,0] op_sel_hi:[1,1,0]
	v_add_f32_dpp v101, v101, v101 quad_perm:[1,0,3,2] row_mask:0xf bank_mask:0xf bound_ctrl:1
	v_fma_mix_f32 v105, v89, v39, 0 op_sel:[1,0,0] op_sel_hi:[1,1,0]
	v_fma_mix_f32 v119, v89, v39, 0 op_sel:[1,1,0] op_sel_hi:[1,1,0]
	v_add_f32_dpp v101, v101, v101 quad_perm:[2,3,0,1] row_mask:0xf bank_mask:0xf bound_ctrl:1
	v_fma_mix_f32 v84, v84, v28, v103 op_sel:[0,0,0] op_sel_hi:[0,1,0]
	v_fma_mix_f32 v85, v85, v28, v104 op_sel:[0,1,0] op_sel_hi:[0,1,0]
	v_add_f32_dpp v101, v101, v101 row_half_mirror row_mask:0xf bank_mask:0xf bound_ctrl:1
	v_fma_mix_f32 v86, v86, v29, v105 op_sel:[0,0,0] op_sel_hi:[0,1,0]
	v_fma_mix_f32 v87, v87, v29, v119 op_sel:[0,1,0] op_sel_hi:[0,1,0]
	v_add_f32_dpp v101, v101, v101 row_mirror row_mask:0xf bank_mask:0xf bound_ctrl:1
	v_fma_mix_f32 v84, -v101, v36, v84 op_sel:[0,0,0] op_sel_hi:[0,1,0]
	v_fma_mix_f32 v85, -v101, v36, v85 op_sel:[0,1,0] op_sel_hi:[0,1,0]
	v_fma_mix_f32 v86, -v101, v37, v86 op_sel:[0,0,0] op_sel_hi:[0,1,0]
	v_fma_mix_f32 v87, -v101, v37, v87 op_sel:[0,1,0] op_sel_hi:[0,1,0]
	v_fma_mix_f32 v99, v84, v22, 0 op_sel:[0,0,0] op_sel_hi:[0,1,0]
	v_cndmask_b32_e64 v187, v97, v96, s[38:39]
	v_fma_mix_f32 v99, v85, v22, v99 op_sel:[0,1,0] op_sel_hi:[0,1,0]
	v_cndmask_b32_e64 v188, v96, v97, s[38:39]
	v_fma_mix_f32 v99, v86, v23, v99 op_sel:[0,0,0] op_sel_hi:[0,1,0]
	v_fma_mix_f32 v99, v87, v23, v99 op_sel:[0,1,0] op_sel_hi:[0,1,0]
	v_cndmask_b32_e64 v189, v99, v98, s[38:39]
	v_cndmask_b32_e64 v190, v98, v99, s[38:39]
	s_waitcnt lgkmcnt(0)
	v_fma_mix_f32 v98, v84, v74, 0 op_sel:[0,0,0] op_sel_hi:[0,1,0]
	v_fma_mix_f32 v98, v85, v74, v98 op_sel:[0,1,0] op_sel_hi:[0,1,0]
	v_add_f32_dpp v188, v188, v187 quad_perm:[1,0,3,2] row_mask:0xf bank_mask:0xf bound_ctrl:1
	v_add_f32_dpp v189, v190, v189 quad_perm:[1,0,3,2] row_mask:0xf bank_mask:0xf bound_ctrl:1
	v_fma_mix_f32 v98, v86, v75, v98 op_sel:[0,0,0] op_sel_hi:[0,1,0]
	v_fma_mix_f32 v98, v87, v75, v98 op_sel:[0,1,0] op_sel_hi:[0,1,0]
	v_cndmask_b32_e64 v191, v189, v188, s[40:41]
	v_cndmask_b32_e64 v192, v188, v189, s[40:41]
	v_fma_mix_f32 v100, v92, v78, 0 op_sel:[0,0,0] op_sel_hi:[1,1,0]
	v_fma_mix_f32 v101, v92, v78, 0 op_sel:[0,1,0] op_sel_hi:[1,1,0]
	v_add_f32_dpp v192, v192, v191 quad_perm:[2,3,0,1] row_mask:0xf bank_mask:0xf bound_ctrl:1
	v_add_f32_dpp v98, v98, v98 quad_perm:[1,0,3,2] row_mask:0xf bank_mask:0xf bound_ctrl:1
	v_fma_mix_f32 v102, v92, v79, 0 op_sel:[0,0,0] op_sel_hi:[1,1,0]
	v_add_f32_dpp v192, v192, v192 row_ror:4 row_mask:0xf bank_mask:0xf bound_ctrl:1
	v_fma_mix_f32 v103, v92, v79, 0 op_sel:[0,1,0] op_sel_hi:[1,1,0]
	v_add_f32_dpp v98, v98, v98 quad_perm:[2,3,0,1] row_mask:0xf bank_mask:0xf bound_ctrl:1
	v_add_f32_dpp v192, v192, v192 row_ror:8 row_mask:0xf bank_mask:0xf bound_ctrl:1
	v_cvt_f16_f32_e32 v192, v192
	global_store_short v83, v192, s[36:37]
	s_add_u32 s36, s36, s44
	s_addc_u32 s37, s37, s45
	s_cmp_gt_i32 s35, 17
	s_cbranch_scc0 .Lc_poll_A7
